# GEMM K-loops: M0-write to LDS-DMA wait state filled by the segment's own ds_read_b128 instead of s_nop (14 fewer idle issue slots per K-iteration)
# speedup vs baseline: 1.0040x; 1.0040x over previous
; #define PG8_STAGE(bufoff, gbase, voff) do { _Pragma("unroll") for (int _i = 0; _i < 2; ++_i) \
;         __builtin_amdgcn_global_load_lds((const unsigned*)((const char*)(gbase) + (voff)[_i]), (LAS unsigned*)(lds + (bufoff) + ldsw + _i * 8192), 16, 0, 0); } while (0)
; #define PG8_LDA(dst, b, h) do { _Pragma("unroll") for (int m = 0; m < 4; ++m) _Pragma("unroll") for (int k = 0; k < 2; ++k) dst[m][k] = *(const LAS bf16x8*)(lds + PG8_SA(b, h) + aoff + m * 2048 + k * 1024); } while (0)
; #define PG8_LDB(dst, b, h) do { _Pragma("unroll") for (int n = 0; n < 2; ++n) _Pragma("unroll") for (int k = 0; k < 2; ++k) dst[n][k] = *(const LAS bf16x8*)(lds + PG8_SB(b, h) + boff + n * 2048 + k * 1024); } while (0)
; #define PG8_MMA(ai, bj, At, Bt) do { __builtin_amdgcn_s_setprio(1); _Pragma("unroll") for (int m = 0; m < 4; ++m) _Pragma("unroll") for (int n = 0; n < 2; ++n) _Pragma("unroll") for (int k = 0; k < 2; ++k) \
;         acc[ai][bj][m][n] = __builtin_amdgcn_mfma_f32_16x16x32_bf16(Bt[n][k], At[m][k], acc[ai][bj][m][n], 0, 0, 0); __builtin_amdgcn_s_setprio(0); } while (0)
; #define PG8_WAIT_V(n) asm volatile("s_waitcnt vmcnt(" #n ")" ::: "memory")
; #define PG8_WAIT_L(n) asm volatile("s_waitcnt lgkmcnt(" #n ")" ::: "memory")
; #define PG8_BAR __builtin_amdgcn_s_barrier()
; #define PG8_SCHED __builtin_amdgcn_sched_barrier(0)
; template <class Epi>
; __device__ __forceinline__ void gemm_phase(LAS unsigned char* lds, const Gemm g, const StaticOrder& S, const Epi& E, const int wid) {
;     ...
;             PG8_LDB(B0, 0, 0); PG8_LDB(B1, 0, 1); PG8_SCHED; PG8_LDA(At, 0, 0); PG8_STAGE(PG8_SA(1, 1), a1 + hstepA, voffA);
;             PG8_WAIT_V(8); PG8_WAIT_L(0); PG8_BAR; PG8_MMA(0, 0, At, B0); PG8_MMA(0, 1, At, B1); PG8_BAR; PG8_SCHED;
;             PG8_LDA(At, 0, 1); PG8_STAGE(PG8_SB(0, 0), b2, voffB); PG8_STAGE(PG8_SB(0, 1), b2 + hstepB, voffB); PG8_STAGE(PG8_SA(0, 0), a2, voffA);
;             PG8_WAIT_V(8); PG8_WAIT_L(0); PG8_BAR; PG8_MMA(1, 0, At, B0); PG8_MMA(1, 1, At, B1); PG8_BAR; PG8_SCHED;
.LBB0_157:
	ds_read_b128 v[150:153], v157
	ds_read_b128 v[160:163], v157 offset:1024
	ds_read_b128 v[164:167], v157 offset:2048
	ds_read_b128 v[168:171], v157 offset:3072
	ds_read_b128 v[172:175], v158
	ds_read_b128 v[176:179], v158 offset:1024
	ds_read_b128 v[180:183], v158 offset:2048
	ds_read_b128 v[184:187], v158 offset:3072
	s_add_u32 s8, s10, 0x100
	s_addc_u32 s9, s11, 0
	s_cmp_eq_u32 s60, 28
	s_cselect_b32 s59, s51, s9
	s_cselect_b32 s58, s50, s8
	s_cselect_b32 s57, s20, s55
	s_cselect_b32 s56, s21, s49
	s_add_i32 m0, s0, 0xc000
	ds_read_b128 v[188:191], v159
	global_load_lds_dwordx4 v142, s[10:11]
	s_add_i32 m0, s0, 0xe000
	ds_read_b128 v[192:195], v159 offset:1024
	global_load_lds_dwordx4 v144, s[10:11]
	ds_read_b128 v[196:199], v159 offset:2048
	ds_read_b128 v[200:203], v159 offset:3072
	ds_read_b128 v[204:207], v159 offset:4096
	ds_read_b128 v[208:211], v159 offset:5120
	ds_read_b128 v[212:215], v159 offset:6144
	ds_read_b128 v[216:219], v159 offset:7168
	s_waitcnt vmcnt(8)
	s_waitcnt lgkmcnt(0)
	s_barrier
	s_setprio 1
	s_waitcnt lgkmcnt(0)
	v_mfma_f32_16x16x32_bf16 v[124:127], v[150:153], v[188:191], v[124:127]
	v_mfma_f32_16x16x32_bf16 v[120:123], v[164:167], v[188:191], v[120:123]
	v_mfma_f32_16x16x32_bf16 v[116:119], v[150:153], v[196:199], v[116:119]
	v_mfma_f32_16x16x32_bf16 v[112:115], v[164:167], v[196:199], v[112:115]
	v_mfma_f32_16x16x32_bf16 v[108:111], v[150:153], v[204:207], v[108:111]
	v_mfma_f32_16x16x32_bf16 v[104:107], v[164:167], v[204:207], v[104:107]
	v_mfma_f32_16x16x32_bf16 v[100:103], v[150:153], v[212:215], v[100:103]
	v_mfma_f32_16x16x32_bf16 v[96:99], v[164:167], v[212:215], v[96:99]
	v_mfma_f32_16x16x32_bf16 v[124:127], v[160:163], v[192:195], v[124:127]
	v_mfma_f32_16x16x32_bf16 v[120:123], v[168:171], v[192:195], v[120:123]
	v_mfma_f32_16x16x32_bf16 v[116:119], v[160:163], v[200:203], v[116:119]
	v_mfma_f32_16x16x32_bf16 v[112:115], v[168:171], v[200:203], v[112:115]
	v_mfma_f32_16x16x32_bf16 v[108:111], v[160:163], v[208:211], v[108:111]
	v_mfma_f32_16x16x32_bf16 v[104:107], v[168:171], v[208:211], v[104:107]
	v_mfma_f32_16x16x32_bf16 v[100:103], v[160:163], v[216:219], v[100:103]
	v_mfma_f32_16x16x32_bf16 v[96:99], v[168:171], v[216:219], v[96:99]
	s_setprio 0
	s_setprio 1
	v_mfma_f32_16x16x32_bf16 v[60:63], v[172:175], v[188:191], v[60:63]
	v_mfma_f32_16x16x32_bf16 v[56:59], v[180:183], v[188:191], v[56:59]
	v_mfma_f32_16x16x32_bf16 v[52:55], v[172:175], v[196:199], v[52:55]
	v_mfma_f32_16x16x32_bf16 v[48:51], v[180:183], v[196:199], v[48:51]
	v_mfma_f32_16x16x32_bf16 v[44:47], v[172:175], v[204:207], v[44:47]
	v_mfma_f32_16x16x32_bf16 v[40:43], v[180:183], v[204:207], v[40:43]
	v_mfma_f32_16x16x32_bf16 v[36:39], v[172:175], v[212:215], v[36:39]
	v_mfma_f32_16x16x32_bf16 v[32:35], v[180:183], v[212:215], v[32:35]
	v_mfma_f32_16x16x32_bf16 v[60:63], v[176:179], v[192:195], v[60:63]
	v_mfma_f32_16x16x32_bf16 v[56:59], v[184:187], v[192:195], v[56:59]
	v_mfma_f32_16x16x32_bf16 v[52:55], v[176:179], v[200:203], v[52:55]
	v_mfma_f32_16x16x32_bf16 v[48:51], v[184:187], v[200:203], v[48:51]
	v_mfma_f32_16x16x32_bf16 v[44:47], v[176:179], v[208:211], v[44:47]
	v_mfma_f32_16x16x32_bf16 v[40:43], v[184:187], v[208:211], v[40:43]
	v_mfma_f32_16x16x32_bf16 v[36:39], v[176:179], v[216:219], v[36:39]
	v_mfma_f32_16x16x32_bf16 v[32:35], v[184:187], v[216:219], v[32:35]
	s_setprio 0
	s_barrier
	s_add_i32 s10, s68, s94
	s_mov_b32 m0, s10
	ds_read_b128 v[188:191], v159 offset:16384
	global_load_lds_dwordx4 v130, s[56:57]
	s_add_i32 m0, s10, 0x2000
	s_add_u32 s10, s56, 0x80000
	s_addc_u32 s11, s57, 0
	s_add_i32 s24, s69, s94
	global_load_lds_dwordx4 v134, s[56:57]
	s_mov_b32 m0, s24
	ds_read_b128 v[192:195], v159 offset:17408
	global_load_lds_dwordx4 v130, s[10:11]
	s_add_i32 m0, s24, 0x2000
	ds_read_b128 v[196:199], v159 offset:18432
	global_load_lds_dwordx4 v134, s[10:11]
	s_mov_b32 m0, s0
	ds_read_b128 v[200:203], v159 offset:19456
	global_load_lds_dwordx4 v128, s[58:59]
	s_mov_b32 m0, s1
	ds_read_b128 v[204:207], v159 offset:20480
	global_load_lds_dwordx4 v132, s[58:59]
	ds_read_b128 v[208:211], v159 offset:21504
	ds_read_b128 v[212:215], v159 offset:22528
	ds_read_b128 v[216:219], v159 offset:23552
	s_waitcnt vmcnt(8)
	s_waitcnt lgkmcnt(0)
	s_barrier
	s_setprio 1
	s_waitcnt lgkmcnt(0)
	v_mfma_f32_16x16x32_bf16 v[92:95], v[150:153], v[188:191], v[92:95]
	v_mfma_f32_16x16x32_bf16 v[88:91], v[164:167], v[188:191], v[88:91]
	v_mfma_f32_16x16x32_bf16 v[84:87], v[150:153], v[196:199], v[84:87]
	v_mfma_f32_16x16x32_bf16 v[80:83], v[164:167], v[196:199], v[80:83]
	v_mfma_f32_16x16x32_bf16 v[76:79], v[150:153], v[204:207], v[76:79]
	v_mfma_f32_16x16x32_bf16 v[72:75], v[164:167], v[204:207], v[72:75]
	v_mfma_f32_16x16x32_bf16 v[68:71], v[150:153], v[212:215], v[68:71]
	v_mfma_f32_16x16x32_bf16 v[64:67], v[164:167], v[212:215], v[64:67]
	v_mfma_f32_16x16x32_bf16 v[92:95], v[160:163], v[192:195], v[92:95]
	v_mfma_f32_16x16x32_bf16 v[88:91], v[168:171], v[192:195], v[88:91]
	v_mfma_f32_16x16x32_bf16 v[84:87], v[160:163], v[200:203], v[84:87]
	v_mfma_f32_16x16x32_bf16 v[80:83], v[168:171], v[200:203], v[80:83]
	v_mfma_f32_16x16x32_bf16 v[76:79], v[160:163], v[208:211], v[76:79]
	v_mfma_f32_16x16x32_bf16 v[72:75], v[168:171], v[208:211], v[72:75]
	v_mfma_f32_16x16x32_bf16 v[68:71], v[160:163], v[216:219], v[68:71]
	v_mfma_f32_16x16x32_bf16 v[64:67], v[168:171], v[216:219], v[64:67]
	s_setprio 0
	s_setprio 1
	v_mfma_f32_16x16x32_bf16 v[28:31], v[172:175], v[188:191], v[28:31]
	v_mfma_f32_16x16x32_bf16 v[24:27], v[180:183], v[188:191], v[24:27]
	v_mfma_f32_16x16x32_bf16 v[20:23], v[172:175], v[196:199], v[20:23]
	v_mfma_f32_16x16x32_bf16 v[16:19], v[180:183], v[196:199], v[16:19]
	v_mfma_f32_16x16x32_bf16 v[12:15], v[172:175], v[204:207], v[12:15]
	v_mfma_f32_16x16x32_bf16 v[8:11], v[180:183], v[204:207], v[8:11]
	v_mfma_f32_16x16x32_bf16 v[4:7], v[172:175], v[212:215], v[4:7]
	v_mfma_f32_16x16x32_bf16 v[0:3], v[180:183], v[212:215], v[0:3]
	v_mfma_f32_16x16x32_bf16 v[28:31], v[176:179], v[192:195], v[28:31]
	v_mfma_f32_16x16x32_bf16 v[24:27], v[184:187], v[192:195], v[24:27]
	v_mfma_f32_16x16x32_bf16 v[20:23], v[176:179], v[200:203], v[20:23]
	v_mfma_f32_16x16x32_bf16 v[16:19], v[184:187], v[200:203], v[16:19]
	v_mfma_f32_16x16x32_bf16 v[12:15], v[176:179], v[208:211], v[12:15]
	v_mfma_f32_16x16x32_bf16 v[8:11], v[184:187], v[208:211], v[8:11]
	v_mfma_f32_16x16x32_bf16 v[4:7], v[176:179], v[216:219], v[4:7]
	v_mfma_f32_16x16x32_bf16 v[0:3], v[184:187], v[216:219], v[0:3]
	s_setprio 0
	s_barrier
; #define PG8_STAGE(bufoff, gbase, voff) do { _Pragma("unroll") for (int _i = 0; _i < 2; ++_i) \
;         __builtin_amdgcn_global_load_lds((const unsigned*)((const char*)(gbase) + (voff)[_i]), (LAS unsigned*)(lds + (bufoff) + ldsw + _i * 8192), 16, 0, 0); } while (0)
; #define PG8_LDA(dst, b, h) do { _Pragma("unroll") for (int m = 0; m < 4; ++m) _Pragma("unroll") for (int k = 0; k < 2; ++k) dst[m][k] = *(const LAS bf16x8*)(lds + PG8_SA(b, h) + aoff + m * 2048 + k * 1024); } while (0)
; #define PG8_LDB(dst, b, h) do { _Pragma("unroll") for (int n = 0; n < 2; ++n) _Pragma("unroll") for (int k = 0; k < 2; ++k) dst[n][k] = *(const LAS bf16x8*)(lds + PG8_SB(b, h) + boff + n * 2048 + k * 1024); } while (0)
; #define PG8_MMA(ai, bj, At, Bt) do { __builtin_amdgcn_s_setprio(1); _Pragma("unroll") for (int m = 0; m < 4; ++m) _Pragma("unroll") for (int n = 0; n < 2; ++n) _Pragma("unroll") for (int k = 0; k < 2; ++k) \
;         acc[ai][bj][m][n] = __builtin_amdgcn_mfma_f32_16x16x32_bf16(Bt[n][k], At[m][k], acc[ai][bj][m][n], 0, 0, 0); __builtin_amdgcn_s_setprio(0); } while (0)
; #define PG8_WAIT_V(n) asm volatile("s_waitcnt vmcnt(" #n ")" ::: "memory")
; #define PG8_WAIT_L(n) asm volatile("s_waitcnt lgkmcnt(" #n ")" ::: "memory")
; #define PG8_BAR __builtin_amdgcn_s_barrier()
; #define PG8_SCHED __builtin_amdgcn_sched_barrier(0)
; template <class Epi>
; __device__ __forceinline__ void gemm_phase(LAS unsigned char* lds, const Gemm g, const StaticOrder& S, const Epi& E, const int wid) {
;     ...
;             PG8_LDB(B0, 1, 0); PG8_LDB(B1, 1, 1); PG8_SCHED; PG8_LDA(At, 1, 0); PG8_STAGE(PG8_SA(0, 1), a2 + hstepA, voffA);
;             PG8_WAIT_V(8); PG8_WAIT_L(0); PG8_BAR; PG8_MMA(0, 0, At, B0); PG8_MMA(0, 1, At, B1); PG8_BAR; PG8_SCHED;
;             PG8_LDA(At, 1, 1); PG8_STAGE(PG8_SB(1, 0), b3, voffB); PG8_STAGE(PG8_SB(1, 1), b3 + hstepB, voffB); PG8_STAGE(PG8_SA(1, 0), a3, voffA);
;             PG8_WAIT_V(8); PG8_WAIT_L(0); PG8_BAR; PG8_MMA(1, 0, At, B0); PG8_MMA(1, 1, At, B1); PG8_BAR; PG8_SCHED;
;         }
	s_add_i32 s24, 0, 0x18000
	v_add_u32_e32 v136, s24, v139
	s_add_i32 s25, 0, 0x1c000
	ds_read_b128 v[150:153], v136
	ds_read_b128 v[160:163], v136 offset:1024
	ds_read_b128 v[164:167], v136 offset:2048
	ds_read_b128 v[168:171], v136 offset:3072
	v_add_u32_e32 v136, s25, v139
	ds_read_b128 v[172:175], v136
	ds_read_b128 v[176:179], v136 offset:1024
	ds_read_b128 v[180:183], v136 offset:2048
	ds_read_b128 v[184:187], v136 offset:3072
	s_add_u32 s10, s58, 0x80000
	s_addc_u32 s11, s59, 0
	s_mov_b32 m0, s15
	ds_read_b128 v[188:191], v159 offset:32768
	global_load_lds_dwordx4 v128, s[10:11]
	s_mov_b32 m0, s26
	ds_read_b128 v[192:195], v159 offset:33792
	global_load_lds_dwordx4 v132, s[10:11]
	ds_read_b128 v[196:199], v159 offset:34816
	ds_read_b128 v[200:203], v159 offset:35840
	ds_read_b128 v[204:207], v159 offset:36864
	ds_read_b128 v[208:211], v159 offset:37888
	ds_read_b128 v[212:215], v159 offset:38912
	ds_read_b128 v[216:219], v159 offset:39936
	s_waitcnt vmcnt(8)
	s_waitcnt lgkmcnt(0)
	s_barrier
	s_setprio 1
	s_waitcnt lgkmcnt(0)
	v_mfma_f32_16x16x32_bf16 v[124:127], v[150:153], v[188:191], v[124:127]
	v_mfma_f32_16x16x32_bf16 v[120:123], v[164:167], v[188:191], v[120:123]
	v_mfma_f32_16x16x32_bf16 v[116:119], v[150:153], v[196:199], v[116:119]
	v_mfma_f32_16x16x32_bf16 v[112:115], v[164:167], v[196:199], v[112:115]
	v_mfma_f32_16x16x32_bf16 v[108:111], v[150:153], v[204:207], v[108:111]
	v_mfma_f32_16x16x32_bf16 v[104:107], v[164:167], v[204:207], v[104:107]
	v_mfma_f32_16x16x32_bf16 v[100:103], v[150:153], v[212:215], v[100:103]
	v_mfma_f32_16x16x32_bf16 v[96:99], v[164:167], v[212:215], v[96:99]
	v_mfma_f32_16x16x32_bf16 v[124:127], v[160:163], v[192:195], v[124:127]
	v_mfma_f32_16x16x32_bf16 v[120:123], v[168:171], v[192:195], v[120:123]
	v_mfma_f32_16x16x32_bf16 v[116:119], v[160:163], v[200:203], v[116:119]
	v_mfma_f32_16x16x32_bf16 v[112:115], v[168:171], v[200:203], v[112:115]
	v_mfma_f32_16x16x32_bf16 v[108:111], v[160:163], v[208:211], v[108:111]
	v_mfma_f32_16x16x32_bf16 v[104:107], v[168:171], v[208:211], v[104:107]
	v_mfma_f32_16x16x32_bf16 v[100:103], v[160:163], v[216:219], v[100:103]
	v_mfma_f32_16x16x32_bf16 v[96:99], v[168:171], v[216:219], v[96:99]
	s_setprio 0
	s_setprio 1
	v_mfma_f32_16x16x32_bf16 v[60:63], v[172:175], v[188:191], v[60:63]
	v_mfma_f32_16x16x32_bf16 v[56:59], v[180:183], v[188:191], v[56:59]
	v_mfma_f32_16x16x32_bf16 v[52:55], v[172:175], v[196:199], v[52:55]
	v_mfma_f32_16x16x32_bf16 v[48:51], v[180:183], v[196:199], v[48:51]
	v_mfma_f32_16x16x32_bf16 v[44:47], v[172:175], v[204:207], v[44:47]
	v_mfma_f32_16x16x32_bf16 v[40:43], v[180:183], v[204:207], v[40:43]
	v_mfma_f32_16x16x32_bf16 v[36:39], v[172:175], v[212:215], v[36:39]
	v_mfma_f32_16x16x32_bf16 v[32:35], v[180:183], v[212:215], v[32:35]
	v_mfma_f32_16x16x32_bf16 v[60:63], v[176:179], v[192:195], v[60:63]
	v_mfma_f32_16x16x32_bf16 v[56:59], v[184:187], v[192:195], v[56:59]
	v_mfma_f32_16x16x32_bf16 v[52:55], v[176:179], v[200:203], v[52:55]
	v_mfma_f32_16x16x32_bf16 v[48:51], v[184:187], v[200:203], v[48:51]
	v_mfma_f32_16x16x32_bf16 v[44:47], v[176:179], v[208:211], v[44:47]
	v_mfma_f32_16x16x32_bf16 v[40:43], v[184:187], v[208:211], v[40:43]
	v_mfma_f32_16x16x32_bf16 v[36:39], v[176:179], v[216:219], v[36:39]
	v_mfma_f32_16x16x32_bf16 v[32:35], v[184:187], v[216:219], v[32:35]
	s_setprio 0
	s_barrier
	s_add_i32 s10, s24, s94
	s_add_u32 s98, s56, 0x80
	s_addc_u32 s99, s57, 0
	s_mov_b32 m0, s10
	ds_read_b128 v[188:191], v159 offset:49152
	global_load_lds_dwordx4 v130, s[98:99]
	s_add_i32 m0, s10, 0x2000
	s_add_u32 s10, s56, 0x80080
	s_addc_u32 s11, s57, 0
	s_add_i32 s24, s25, s94
	global_load_lds_dwordx4 v134, s[98:99]
	s_mov_b32 m0, s24
	ds_read_b128 v[192:195], v159 offset:50176
	global_load_lds_dwordx4 v130, s[10:11]
	s_add_i32 m0, s24, 0x2000
	ds_read_b128 v[196:199], v159 offset:51200
	global_load_lds_dwordx4 v134, s[10:11]
	s_add_u32 s100, s58, 0x80
	s_addc_u32 s101, s59, 0
	s_mov_b32 m0, s66
	ds_read_b128 v[200:203], v159 offset:52224
	global_load_lds_dwordx4 v128, s[100:101]
	s_mov_b32 m0, s67
	ds_read_b128 v[204:207], v159 offset:53248
	global_load_lds_dwordx4 v132, s[100:101]
	ds_read_b128 v[208:211], v159 offset:54272
	ds_read_b128 v[212:215], v159 offset:55296
	ds_read_b128 v[216:219], v159 offset:56320
	s_waitcnt vmcnt(8)
	s_waitcnt lgkmcnt(0)
	s_barrier
	s_setprio 1
	s_waitcnt lgkmcnt(0)
	v_mfma_f32_16x16x32_bf16 v[92:95], v[150:153], v[188:191], v[92:95]
	v_mfma_f32_16x16x32_bf16 v[88:91], v[164:167], v[188:191], v[88:91]
	v_mfma_f32_16x16x32_bf16 v[84:87], v[150:153], v[196:199], v[84:87]
	v_mfma_f32_16x16x32_bf16 v[80:83], v[164:167], v[196:199], v[80:83]
	v_mfma_f32_16x16x32_bf16 v[76:79], v[150:153], v[204:207], v[76:79]
	v_mfma_f32_16x16x32_bf16 v[72:75], v[164:167], v[204:207], v[72:75]
	v_mfma_f32_16x16x32_bf16 v[68:71], v[150:153], v[212:215], v[68:71]
	v_mfma_f32_16x16x32_bf16 v[64:67], v[164:167], v[212:215], v[64:67]
	v_mfma_f32_16x16x32_bf16 v[92:95], v[160:163], v[192:195], v[92:95]
	v_mfma_f32_16x16x32_bf16 v[88:91], v[168:171], v[192:195], v[88:91]
	v_mfma_f32_16x16x32_bf16 v[84:87], v[160:163], v[200:203], v[84:87]
	v_mfma_f32_16x16x32_bf16 v[80:83], v[168:171], v[200:203], v[80:83]
	v_mfma_f32_16x16x32_bf16 v[76:79], v[160:163], v[208:211], v[76:79]
	v_mfma_f32_16x16x32_bf16 v[72:75], v[168:171], v[208:211], v[72:75]
	v_mfma_f32_16x16x32_bf16 v[68:71], v[160:163], v[216:219], v[68:71]
	v_mfma_f32_16x16x32_bf16 v[64:67], v[168:171], v[216:219], v[64:67]
	s_setprio 0
	s_setprio 1
	v_mfma_f32_16x16x32_bf16 v[28:31], v[172:175], v[188:191], v[28:31]
	v_mfma_f32_16x16x32_bf16 v[24:27], v[180:183], v[188:191], v[24:27]
	v_mfma_f32_16x16x32_bf16 v[20:23], v[172:175], v[196:199], v[20:23]
	v_mfma_f32_16x16x32_bf16 v[16:19], v[180:183], v[196:199], v[16:19]
	v_mfma_f32_16x16x32_bf16 v[12:15], v[172:175], v[204:207], v[12:15]
	v_mfma_f32_16x16x32_bf16 v[8:11], v[180:183], v[204:207], v[8:11]
	v_mfma_f32_16x16x32_bf16 v[4:7], v[172:175], v[212:215], v[4:7]
	v_mfma_f32_16x16x32_bf16 v[0:3], v[180:183], v[212:215], v[0:3]
	v_mfma_f32_16x16x32_bf16 v[28:31], v[176:179], v[192:195], v[28:31]
	v_mfma_f32_16x16x32_bf16 v[24:27], v[184:187], v[192:195], v[24:27]
	v_mfma_f32_16x16x32_bf16 v[20:23], v[176:179], v[200:203], v[20:23]
	v_mfma_f32_16x16x32_bf16 v[16:19], v[184:187], v[200:203], v[16:19]
	v_mfma_f32_16x16x32_bf16 v[12:15], v[176:179], v[208:211], v[12:15]
	v_mfma_f32_16x16x32_bf16 v[8:11], v[184:187], v[208:211], v[8:11]
	v_mfma_f32_16x16x32_bf16 v[4:7], v[176:179], v[216:219], v[4:7]
	v_mfma_f32_16x16x32_bf16 v[0:3], v[184:187], v[216:219], v[0:3]
	s_setprio 0
	s_barrier
	s_add_i32 s60, s60, 2
	s_add_u32 s49, s49, 0x100
	s_addc_u32 s55, s55, 0
	s_cmp_gt_u32 s60, 29
	s_mov_b64 s[10:11], s[8:9]
	s_cbranch_scc0 .LBB0_157
	s_and_b64 vcc, exec, s[22:23]
	s_cbranch_vccz .LBB0_160
	s_barrier

; #define PG8_STAGE(bufoff, gbase, voff) do { _Pragma("unroll") for (int _i = 0; _i < 2; ++_i) \
;         __builtin_amdgcn_global_load_lds((const unsigned*)((const char*)(gbase) + (voff)[_i]), (LAS unsigned*)(lds + (bufoff) + ldsw + _i * 8192), 16, 0, 0); } while (0)
; #define PG8_LDA(dst, b, h) do { _Pragma("unroll") for (int m = 0; m < 4; ++m) _Pragma("unroll") for (int k = 0; k < 2; ++k) dst[m][k] = *(const LAS bf16x8*)(lds + PG8_SA(b, h) + aoff + m * 2048 + k * 1024); } while (0)
; #define PG8_LDB(dst, b, h) do { _Pragma("unroll") for (int n = 0; n < 2; ++n) _Pragma("unroll") for (int k = 0; k < 2; ++k) dst[n][k] = *(const LAS bf16x8*)(lds + PG8_SB(b, h) + boff + n * 2048 + k * 1024); } while (0)
; #define PG8_MMA(ai, bj, At, Bt) do { __builtin_amdgcn_s_setprio(1); _Pragma("unroll") for (int m = 0; m < 4; ++m) _Pragma("unroll") for (int n = 0; n < 2; ++n) _Pragma("unroll") for (int k = 0; k < 2; ++k) \
;         acc[ai][bj][m][n] = __builtin_amdgcn_mfma_f32_16x16x32_bf16(Bt[n][k], At[m][k], acc[ai][bj][m][n], 0, 0, 0); __builtin_amdgcn_s_setprio(0); } while (0)
; #define PG8_WAIT_V(n) asm volatile("s_waitcnt vmcnt(" #n ")" ::: "memory")
; #define PG8_WAIT_L(n) asm volatile("s_waitcnt lgkmcnt(" #n ")" ::: "memory")
; #define PG8_BAR __builtin_amdgcn_s_barrier()
; #define PG8_SCHED __builtin_amdgcn_sched_barrier(0)
; template <class Epi>
; __device__ __forceinline__ void gemm_phase(LAS unsigned char* lds, const Gemm g, const StaticOrder& S, const Epi& E, const int wid) {
;     ...
;             PG8_LDB(B0, 0, 0); PG8_LDB(B1, 0, 1); PG8_SCHED; PG8_LDA(At, 0, 0); PG8_STAGE(PG8_SA(1, 1), a1 + hstepA, voffA);
;             PG8_WAIT_V(8); PG8_WAIT_L(0); PG8_BAR; PG8_MMA(0, 0, At, B0); PG8_MMA(0, 1, At, B1); PG8_BAR; PG8_SCHED;
;             PG8_LDA(At, 0, 1); PG8_STAGE(PG8_SB(0, 0), b2, voffB); PG8_STAGE(PG8_SB(0, 1), b2 + hstepB, voffB); PG8_STAGE(PG8_SA(0, 0), a2, voffA);
;             PG8_WAIT_V(8); PG8_WAIT_L(0); PG8_BAR; PG8_MMA(1, 0, At, B0); PG8_MMA(1, 1, At, B1); PG8_BAR; PG8_SCHED;
.LBB0_1669:
	ds_read_b128 v[144:147], v157
	ds_read_b128 v[148:151], v157 offset:1024
	ds_read_b128 v[160:163], v157 offset:2048
	ds_read_b128 v[164:167], v157 offset:3072
	ds_read_b128 v[168:171], v158
	ds_read_b128 v[172:175], v158 offset:1024
	ds_read_b128 v[176:179], v158 offset:2048
	ds_read_b128 v[180:183], v158 offset:3072
	s_add_u32 s6, s46, 0x100
	s_addc_u32 s7, s47, 0
	s_cmp_eq_u32 s55, 12
	s_cselect_b32 s51, s43, s7
	s_cselect_b32 s50, s42, s6
	s_cselect_b32 s49, s11, s54
	s_cselect_b32 s48, s21, s53
	s_add_i32 m0, s0, 0xc000
	ds_read_b128 v[184:187], v159
	global_load_lds_dwordx4 v136, s[46:47]
	s_add_i32 m0, s0, 0xe000
	ds_read_b128 v[188:191], v159 offset:1024
	global_load_lds_dwordx4 v138, s[46:47]
	ds_read_b128 v[192:195], v159 offset:2048
	ds_read_b128 v[196:199], v159 offset:3072
	ds_read_b128 v[200:203], v159 offset:4096
	ds_read_b128 v[204:207], v159 offset:5120
	ds_read_b128 v[208:211], v159 offset:6144
	ds_read_b128 v[212:215], v159 offset:7168
	s_waitcnt vmcnt(8)
	s_waitcnt lgkmcnt(0)
	s_barrier
	s_setprio 1
	s_waitcnt lgkmcnt(0)
	v_mfma_f32_16x16x32_bf16 v[124:127], v[144:147], v[184:187], v[124:127]
	v_mfma_f32_16x16x32_bf16 v[120:123], v[160:163], v[184:187], v[120:123]
	v_mfma_f32_16x16x32_bf16 v[116:119], v[144:147], v[192:195], v[116:119]
	v_mfma_f32_16x16x32_bf16 v[112:115], v[160:163], v[192:195], v[112:115]
	v_mfma_f32_16x16x32_bf16 v[108:111], v[144:147], v[200:203], v[108:111]
	v_mfma_f32_16x16x32_bf16 v[104:107], v[160:163], v[200:203], v[104:107]
	v_mfma_f32_16x16x32_bf16 v[100:103], v[144:147], v[208:211], v[100:103]
	v_mfma_f32_16x16x32_bf16 v[96:99], v[160:163], v[208:211], v[96:99]
	v_mfma_f32_16x16x32_bf16 v[124:127], v[148:151], v[188:191], v[124:127]
	v_mfma_f32_16x16x32_bf16 v[120:123], v[164:167], v[188:191], v[120:123]
	v_mfma_f32_16x16x32_bf16 v[116:119], v[148:151], v[196:199], v[116:119]
	v_mfma_f32_16x16x32_bf16 v[112:115], v[164:167], v[196:199], v[112:115]
	v_mfma_f32_16x16x32_bf16 v[108:111], v[148:151], v[204:207], v[108:111]
	v_mfma_f32_16x16x32_bf16 v[104:107], v[164:167], v[204:207], v[104:107]
	v_mfma_f32_16x16x32_bf16 v[100:103], v[148:151], v[212:215], v[100:103]
	v_mfma_f32_16x16x32_bf16 v[96:99], v[164:167], v[212:215], v[96:99]
	s_setprio 0
	s_setprio 1
	v_mfma_f32_16x16x32_bf16 v[68:71], v[168:171], v[184:187], v[68:71]
	v_mfma_f32_16x16x32_bf16 v[60:63], v[176:179], v[184:187], v[60:63]
	v_mfma_f32_16x16x32_bf16 v[52:55], v[168:171], v[192:195], v[52:55]
	v_mfma_f32_16x16x32_bf16 v[48:51], v[176:179], v[192:195], v[48:51]
	v_mfma_f32_16x16x32_bf16 v[44:47], v[168:171], v[200:203], v[44:47]
	v_mfma_f32_16x16x32_bf16 v[40:43], v[176:179], v[200:203], v[40:43]
	v_mfma_f32_16x16x32_bf16 v[36:39], v[168:171], v[208:211], v[36:39]
	v_mfma_f32_16x16x32_bf16 v[32:35], v[176:179], v[208:211], v[32:35]
	v_mfma_f32_16x16x32_bf16 v[68:71], v[172:175], v[188:191], v[68:71]
	v_mfma_f32_16x16x32_bf16 v[60:63], v[180:183], v[188:191], v[60:63]
	v_mfma_f32_16x16x32_bf16 v[52:55], v[172:175], v[196:199], v[52:55]
	v_mfma_f32_16x16x32_bf16 v[48:51], v[180:183], v[196:199], v[48:51]
	v_mfma_f32_16x16x32_bf16 v[44:47], v[172:175], v[204:207], v[44:47]
	v_mfma_f32_16x16x32_bf16 v[40:43], v[180:183], v[204:207], v[40:43]
	v_mfma_f32_16x16x32_bf16 v[36:39], v[172:175], v[212:215], v[36:39]
	v_mfma_f32_16x16x32_bf16 v[32:35], v[180:183], v[212:215], v[32:35]
	s_setprio 0
	s_barrier
	s_add_i32 s24, s36, s94
	s_mov_b32 m0, s24
	ds_read_b128 v[184:187], v159 offset:16384
	global_load_lds_dwordx4 v132, s[48:49]
	s_add_i32 m0, s24, 0x2000
	s_add_u32 s24, s48, 0x40000
	s_addc_u32 s25, s49, 0
	s_add_i32 s46, s37, s94
	global_load_lds_dwordx4 v128, s[48:49]
	s_mov_b32 m0, s46
	ds_read_b128 v[188:191], v159 offset:17408
	global_load_lds_dwordx4 v132, s[24:25]
	s_add_i32 m0, s46, 0x2000
	ds_read_b128 v[192:195], v159 offset:18432
	global_load_lds_dwordx4 v128, s[24:25]
	s_mov_b32 m0, s0
	ds_read_b128 v[196:199], v159 offset:19456
	global_load_lds_dwordx4 v134, s[50:51]
	s_mov_b32 m0, s1
	ds_read_b128 v[200:203], v159 offset:20480
	global_load_lds_dwordx4 v130, s[50:51]
	ds_read_b128 v[204:207], v159 offset:21504
	ds_read_b128 v[208:211], v159 offset:22528
	ds_read_b128 v[212:215], v159 offset:23552
	s_waitcnt vmcnt(8)
	s_waitcnt lgkmcnt(0)
	s_barrier
	s_setprio 1
	s_waitcnt lgkmcnt(0)
	v_mfma_f32_16x16x32_bf16 v[92:95], v[144:147], v[184:187], v[92:95]
	v_mfma_f32_16x16x32_bf16 v[88:91], v[160:163], v[184:187], v[88:91]
	v_mfma_f32_16x16x32_bf16 v[84:87], v[144:147], v[192:195], v[84:87]
	v_mfma_f32_16x16x32_bf16 v[80:83], v[160:163], v[192:195], v[80:83]
	v_mfma_f32_16x16x32_bf16 v[76:79], v[144:147], v[200:203], v[76:79]
	v_mfma_f32_16x16x32_bf16 v[72:75], v[160:163], v[200:203], v[72:75]
	v_mfma_f32_16x16x32_bf16 v[64:67], v[144:147], v[208:211], v[64:67]
	v_mfma_f32_16x16x32_bf16 v[56:59], v[160:163], v[208:211], v[56:59]
	v_mfma_f32_16x16x32_bf16 v[92:95], v[148:151], v[188:191], v[92:95]
	v_mfma_f32_16x16x32_bf16 v[88:91], v[164:167], v[188:191], v[88:91]
	v_mfma_f32_16x16x32_bf16 v[84:87], v[148:151], v[196:199], v[84:87]
	v_mfma_f32_16x16x32_bf16 v[80:83], v[164:167], v[196:199], v[80:83]
	v_mfma_f32_16x16x32_bf16 v[76:79], v[148:151], v[204:207], v[76:79]
	v_mfma_f32_16x16x32_bf16 v[72:75], v[164:167], v[204:207], v[72:75]
	v_mfma_f32_16x16x32_bf16 v[64:67], v[148:151], v[212:215], v[64:67]
	v_mfma_f32_16x16x32_bf16 v[56:59], v[164:167], v[212:215], v[56:59]
	s_setprio 0
	s_setprio 1
	v_mfma_f32_16x16x32_bf16 v[28:31], v[168:171], v[184:187], v[28:31]
	v_mfma_f32_16x16x32_bf16 v[24:27], v[176:179], v[184:187], v[24:27]
	v_mfma_f32_16x16x32_bf16 v[20:23], v[168:171], v[192:195], v[20:23]
	v_mfma_f32_16x16x32_bf16 v[16:19], v[176:179], v[192:195], v[16:19]
	v_mfma_f32_16x16x32_bf16 v[12:15], v[168:171], v[200:203], v[12:15]
	v_mfma_f32_16x16x32_bf16 v[8:11], v[176:179], v[200:203], v[8:11]
	v_mfma_f32_16x16x32_bf16 v[4:7], v[168:171], v[208:211], v[4:7]
	v_mfma_f32_16x16x32_bf16 v[0:3], v[176:179], v[208:211], v[0:3]
	v_mfma_f32_16x16x32_bf16 v[28:31], v[172:175], v[188:191], v[28:31]
	v_mfma_f32_16x16x32_bf16 v[24:27], v[180:183], v[188:191], v[24:27]
	v_mfma_f32_16x16x32_bf16 v[20:23], v[172:175], v[196:199], v[20:23]
	v_mfma_f32_16x16x32_bf16 v[16:19], v[180:183], v[196:199], v[16:19]
	v_mfma_f32_16x16x32_bf16 v[12:15], v[172:175], v[204:207], v[12:15]
	v_mfma_f32_16x16x32_bf16 v[8:11], v[180:183], v[204:207], v[8:11]
	v_mfma_f32_16x16x32_bf16 v[4:7], v[172:175], v[212:215], v[4:7]
	v_mfma_f32_16x16x32_bf16 v[0:3], v[180:183], v[212:215], v[0:3]
	s_setprio 0
	s_barrier
; #define PG8_STAGE(bufoff, gbase, voff) do { _Pragma("unroll") for (int _i = 0; _i < 2; ++_i) \
;         __builtin_amdgcn_global_load_lds((const unsigned*)((const char*)(gbase) + (voff)[_i]), (LAS unsigned*)(lds + (bufoff) + ldsw + _i * 8192), 16, 0, 0); } while (0)
; #define PG8_LDA(dst, b, h) do { _Pragma("unroll") for (int m = 0; m < 4; ++m) _Pragma("unroll") for (int k = 0; k < 2; ++k) dst[m][k] = *(const LAS bf16x8*)(lds + PG8_SA(b, h) + aoff + m * 2048 + k * 1024); } while (0)
; #define PG8_LDB(dst, b, h) do { _Pragma("unroll") for (int n = 0; n < 2; ++n) _Pragma("unroll") for (int k = 0; k < 2; ++k) dst[n][k] = *(const LAS bf16x8*)(lds + PG8_SB(b, h) + boff + n * 2048 + k * 1024); } while (0)
; #define PG8_MMA(ai, bj, At, Bt) do { __builtin_amdgcn_s_setprio(1); _Pragma("unroll") for (int m = 0; m < 4; ++m) _Pragma("unroll") for (int n = 0; n < 2; ++n) _Pragma("unroll") for (int k = 0; k < 2; ++k) \
;         acc[ai][bj][m][n] = __builtin_amdgcn_mfma_f32_16x16x32_bf16(Bt[n][k], At[m][k], acc[ai][bj][m][n], 0, 0, 0); __builtin_amdgcn_s_setprio(0); } while (0)
; #define PG8_WAIT_V(n) asm volatile("s_waitcnt vmcnt(" #n ")" ::: "memory")
; #define PG8_WAIT_L(n) asm volatile("s_waitcnt lgkmcnt(" #n ")" ::: "memory")
; #define PG8_BAR __builtin_amdgcn_s_barrier()
; #define PG8_SCHED __builtin_amdgcn_sched_barrier(0)
; template <class Epi>
; __device__ __forceinline__ void gemm_phase(LAS unsigned char* lds, const Gemm g, const StaticOrder& S, const Epi& E, const int wid) {
;     ...
;             PG8_LDB(B0, 1, 0); PG8_LDB(B1, 1, 1); PG8_SCHED; PG8_LDA(At, 1, 0); PG8_STAGE(PG8_SA(0, 1), a2 + hstepA, voffA);
;             PG8_WAIT_V(8); PG8_WAIT_L(0); PG8_BAR; PG8_MMA(0, 0, At, B0); PG8_MMA(0, 1, At, B1); PG8_BAR; PG8_SCHED;
;             PG8_LDA(At, 1, 1); PG8_STAGE(PG8_SB(1, 0), b3, voffB); PG8_STAGE(PG8_SB(1, 1), b3 + hstepB, voffB); PG8_STAGE(PG8_SA(1, 0), a3, voffA);
;             PG8_WAIT_V(8); PG8_WAIT_L(0); PG8_BAR; PG8_MMA(1, 0, At, B0); PG8_MMA(1, 1, At, B1); PG8_BAR; PG8_SCHED;
;         }
	s_add_i32 s46, 0, 0x18000
	s_add_i32 s47, 0, 0x1c000
	v_add_u32_e32 v164, s46, v154
	v_add_u32_e32 v180, s47, v154
	ds_read_b128 v[144:147], v164
	ds_read_b128 v[148:151], v164 offset:1024
	ds_read_b128 v[160:163], v164 offset:2048
	ds_read_b128 v[164:167], v164 offset:3072
	ds_read_b128 v[168:171], v180
	ds_read_b128 v[172:175], v180 offset:1024
	ds_read_b128 v[176:179], v180 offset:2048
	ds_read_b128 v[180:183], v180 offset:3072
	s_add_u32 s24, s50, 0x40000
	s_addc_u32 s25, s51, 0
	s_mov_b32 m0, s15
	ds_read_b128 v[184:187], v159 offset:32768
	global_load_lds_dwordx4 v134, s[24:25]
	s_mov_b32 m0, s26
	ds_read_b128 v[188:191], v159 offset:33792
	global_load_lds_dwordx4 v130, s[24:25]
	ds_read_b128 v[192:195], v159 offset:34816
	ds_read_b128 v[196:199], v159 offset:35840
	ds_read_b128 v[200:203], v159 offset:36864
	ds_read_b128 v[204:207], v159 offset:37888
	ds_read_b128 v[208:211], v159 offset:38912
	ds_read_b128 v[212:215], v159 offset:39936
	s_waitcnt vmcnt(8)
	s_waitcnt lgkmcnt(0)
	s_barrier
	s_setprio 1
	s_waitcnt lgkmcnt(0)
	v_mfma_f32_16x16x32_bf16 v[124:127], v[144:147], v[184:187], v[124:127]
	v_mfma_f32_16x16x32_bf16 v[120:123], v[160:163], v[184:187], v[120:123]
	v_mfma_f32_16x16x32_bf16 v[116:119], v[144:147], v[192:195], v[116:119]
	v_mfma_f32_16x16x32_bf16 v[112:115], v[160:163], v[192:195], v[112:115]
	v_mfma_f32_16x16x32_bf16 v[108:111], v[144:147], v[200:203], v[108:111]
	v_mfma_f32_16x16x32_bf16 v[104:107], v[160:163], v[200:203], v[104:107]
	v_mfma_f32_16x16x32_bf16 v[100:103], v[144:147], v[208:211], v[100:103]
	v_mfma_f32_16x16x32_bf16 v[96:99], v[160:163], v[208:211], v[96:99]
	v_mfma_f32_16x16x32_bf16 v[124:127], v[148:151], v[188:191], v[124:127]
	v_mfma_f32_16x16x32_bf16 v[120:123], v[164:167], v[188:191], v[120:123]
	v_mfma_f32_16x16x32_bf16 v[116:119], v[148:151], v[196:199], v[116:119]
	v_mfma_f32_16x16x32_bf16 v[112:115], v[164:167], v[196:199], v[112:115]
	v_mfma_f32_16x16x32_bf16 v[108:111], v[148:151], v[204:207], v[108:111]
	v_mfma_f32_16x16x32_bf16 v[104:107], v[164:167], v[204:207], v[104:107]
	v_mfma_f32_16x16x32_bf16 v[100:103], v[148:151], v[212:215], v[100:103]
	v_mfma_f32_16x16x32_bf16 v[96:99], v[164:167], v[212:215], v[96:99]
	s_setprio 0
	s_setprio 1
	v_mfma_f32_16x16x32_bf16 v[68:71], v[168:171], v[184:187], v[68:71]
	v_mfma_f32_16x16x32_bf16 v[60:63], v[176:179], v[184:187], v[60:63]
	v_mfma_f32_16x16x32_bf16 v[52:55], v[168:171], v[192:195], v[52:55]
	v_mfma_f32_16x16x32_bf16 v[48:51], v[176:179], v[192:195], v[48:51]
	v_mfma_f32_16x16x32_bf16 v[44:47], v[168:171], v[200:203], v[44:47]
	v_mfma_f32_16x16x32_bf16 v[40:43], v[176:179], v[200:203], v[40:43]
	v_mfma_f32_16x16x32_bf16 v[36:39], v[168:171], v[208:211], v[36:39]
	v_mfma_f32_16x16x32_bf16 v[32:35], v[176:179], v[208:211], v[32:35]
	v_mfma_f32_16x16x32_bf16 v[68:71], v[172:175], v[188:191], v[68:71]
	v_mfma_f32_16x16x32_bf16 v[60:63], v[180:183], v[188:191], v[60:63]
	v_mfma_f32_16x16x32_bf16 v[52:55], v[172:175], v[196:199], v[52:55]
	v_mfma_f32_16x16x32_bf16 v[48:51], v[180:183], v[196:199], v[48:51]
	v_mfma_f32_16x16x32_bf16 v[44:47], v[172:175], v[204:207], v[44:47]
	v_mfma_f32_16x16x32_bf16 v[40:43], v[180:183], v[204:207], v[40:43]
	v_mfma_f32_16x16x32_bf16 v[36:39], v[172:175], v[212:215], v[36:39]
	v_mfma_f32_16x16x32_bf16 v[32:35], v[180:183], v[212:215], v[32:35]
	s_setprio 0
	s_barrier
	s_add_i32 s24, s46, s94
	s_add_u32 s98, s48, 0x80
	s_addc_u32 s99, s49, 0
	s_mov_b32 m0, s24
	ds_read_b128 v[184:187], v159 offset:49152
	global_load_lds_dwordx4 v132, s[98:99]
	s_add_i32 m0, s24, 0x2000
	s_add_u32 s24, s48, 0x40080
	s_addc_u32 s25, s49, 0
	s_add_i32 s46, s47, s94
	global_load_lds_dwordx4 v128, s[98:99]
	s_mov_b32 m0, s46
	ds_read_b128 v[188:191], v159 offset:50176
	global_load_lds_dwordx4 v132, s[24:25]
	s_add_i32 m0, s46, 0x2000
	ds_read_b128 v[192:195], v159 offset:51200
	global_load_lds_dwordx4 v128, s[24:25]
	s_add_u32 s100, s50, 0x80
	s_addc_u32 s101, s51, 0
	s_mov_b32 m0, s28
	ds_read_b128 v[196:199], v159 offset:52224
	global_load_lds_dwordx4 v134, s[100:101]
	s_mov_b32 m0, s29
	ds_read_b128 v[200:203], v159 offset:53248
	global_load_lds_dwordx4 v130, s[100:101]
	ds_read_b128 v[204:207], v159 offset:54272
	ds_read_b128 v[208:211], v159 offset:55296
	ds_read_b128 v[212:215], v159 offset:56320
	s_waitcnt vmcnt(8)
	s_waitcnt lgkmcnt(0)
	s_barrier
	s_setprio 1
	s_waitcnt lgkmcnt(0)
	v_mfma_f32_16x16x32_bf16 v[92:95], v[144:147], v[184:187], v[92:95]
	v_mfma_f32_16x16x32_bf16 v[88:91], v[160:163], v[184:187], v[88:91]
	v_mfma_f32_16x16x32_bf16 v[84:87], v[144:147], v[192:195], v[84:87]
	v_mfma_f32_16x16x32_bf16 v[80:83], v[160:163], v[192:195], v[80:83]
	v_mfma_f32_16x16x32_bf16 v[76:79], v[144:147], v[200:203], v[76:79]
	v_mfma_f32_16x16x32_bf16 v[72:75], v[160:163], v[200:203], v[72:75]
	v_mfma_f32_16x16x32_bf16 v[64:67], v[144:147], v[208:211], v[64:67]
	v_mfma_f32_16x16x32_bf16 v[56:59], v[160:163], v[208:211], v[56:59]
	v_mfma_f32_16x16x32_bf16 v[92:95], v[148:151], v[188:191], v[92:95]
	v_mfma_f32_16x16x32_bf16 v[88:91], v[164:167], v[188:191], v[88:91]
	v_mfma_f32_16x16x32_bf16 v[84:87], v[148:151], v[196:199], v[84:87]
	v_mfma_f32_16x16x32_bf16 v[80:83], v[164:167], v[196:199], v[80:83]
	v_mfma_f32_16x16x32_bf16 v[76:79], v[148:151], v[204:207], v[76:79]
	v_mfma_f32_16x16x32_bf16 v[72:75], v[164:167], v[204:207], v[72:75]
	v_mfma_f32_16x16x32_bf16 v[64:67], v[148:151], v[212:215], v[64:67]
	v_mfma_f32_16x16x32_bf16 v[56:59], v[164:167], v[212:215], v[56:59]
	s_setprio 0
	s_setprio 1
	v_mfma_f32_16x16x32_bf16 v[28:31], v[168:171], v[184:187], v[28:31]
	v_mfma_f32_16x16x32_bf16 v[24:27], v[176:179], v[184:187], v[24:27]
	v_mfma_f32_16x16x32_bf16 v[20:23], v[168:171], v[192:195], v[20:23]
	v_mfma_f32_16x16x32_bf16 v[16:19], v[176:179], v[192:195], v[16:19]
	v_mfma_f32_16x16x32_bf16 v[12:15], v[168:171], v[200:203], v[12:15]
	v_mfma_f32_16x16x32_bf16 v[8:11], v[176:179], v[200:203], v[8:11]
	v_mfma_f32_16x16x32_bf16 v[4:7], v[168:171], v[208:211], v[4:7]
	v_mfma_f32_16x16x32_bf16 v[0:3], v[176:179], v[208:211], v[0:3]
	v_mfma_f32_16x16x32_bf16 v[28:31], v[172:175], v[188:191], v[28:31]
	v_mfma_f32_16x16x32_bf16 v[24:27], v[180:183], v[188:191], v[24:27]
	v_mfma_f32_16x16x32_bf16 v[20:23], v[172:175], v[196:199], v[20:23]
	v_mfma_f32_16x16x32_bf16 v[16:19], v[180:183], v[196:199], v[16:19]
	v_mfma_f32_16x16x32_bf16 v[12:15], v[172:175], v[204:207], v[12:15]
	v_mfma_f32_16x16x32_bf16 v[8:11], v[180:183], v[204:207], v[8:11]
	v_mfma_f32_16x16x32_bf16 v[4:7], v[172:175], v[212:215], v[4:7]
	v_mfma_f32_16x16x32_bf16 v[0:3], v[180:183], v[212:215], v[0:3]
	s_setprio 0
	s_barrier
	s_add_i32 s55, s55, 2
	s_add_u32 s53, s53, 0x100
	s_addc_u32 s54, s54, 0
	s_cmp_gt_u32 s55, 13
	s_mov_b64 s[46:47], s[6:7]
	s_cbranch_scc0 .LBB0_1669
	s_and_b64 vcc, exec, s[22:23]
	s_cbranch_vccz .LBB0_1672
	s_barrier

; #define PG8_STAGE(bufoff, gbase, voff) do { _Pragma("unroll") for (int _i = 0; _i < 2; ++_i) \
;         __builtin_amdgcn_global_load_lds((const unsigned*)((const char*)(gbase) + (voff)[_i]), (LAS unsigned*)(lds + (bufoff) + ldsw + _i * 8192), 16, 0, 0); } while (0)
; #define PG8_LDA(dst, b, h) do { _Pragma("unroll") for (int m = 0; m < 4; ++m) _Pragma("unroll") for (int k = 0; k < 2; ++k) dst[m][k] = *(const LAS bf16x8*)(lds + PG8_SA(b, h) + aoff + m * 2048 + k * 1024); } while (0)
; #define PG8_LDB(dst, b, h) do { _Pragma("unroll") for (int n = 0; n < 2; ++n) _Pragma("unroll") for (int k = 0; k < 2; ++k) dst[n][k] = *(const LAS bf16x8*)(lds + PG8_SB(b, h) + boff + n * 2048 + k * 1024); } while (0)
; #define PG8_MMA(ai, bj, At, Bt) do { __builtin_amdgcn_s_setprio(1); _Pragma("unroll") for (int m = 0; m < 4; ++m) _Pragma("unroll") for (int n = 0; n < 2; ++n) _Pragma("unroll") for (int k = 0; k < 2; ++k) \
;         acc[ai][bj][m][n] = __builtin_amdgcn_mfma_f32_16x16x32_bf16(Bt[n][k], At[m][k], acc[ai][bj][m][n], 0, 0, 0); __builtin_amdgcn_s_setprio(0); } while (0)
; #define PG8_WAIT_V(n) asm volatile("s_waitcnt vmcnt(" #n ")" ::: "memory")
; #define PG8_WAIT_L(n) asm volatile("s_waitcnt lgkmcnt(" #n ")" ::: "memory")
; #define PG8_BAR __builtin_amdgcn_s_barrier()
; #define PG8_SCHED __builtin_amdgcn_sched_barrier(0)
; template <class Epi>
; __device__ __forceinline__ void gemm_phase(LAS unsigned char* lds, const Gemm g, const StaticOrder& S, const Epi& E, const int wid) {
;     ...
;             PG8_LDB(B0, 0, 0); PG8_LDB(B1, 0, 1); PG8_SCHED; PG8_LDA(At, 0, 0); PG8_STAGE(PG8_SA(1, 1), a1 + hstepA, voffA);
;             PG8_WAIT_V(8); PG8_WAIT_L(0); PG8_BAR; PG8_MMA(0, 0, At, B0); PG8_MMA(0, 1, At, B1); PG8_BAR; PG8_SCHED;
;             PG8_LDA(At, 0, 1); PG8_STAGE(PG8_SB(0, 0), b2, voffB); PG8_STAGE(PG8_SB(0, 1), b2 + hstepB, voffB); PG8_STAGE(PG8_SA(0, 0), a2, voffA);
;             PG8_WAIT_V(8); PG8_WAIT_L(0); PG8_BAR; PG8_MMA(1, 0, At, B0); PG8_MMA(1, 1, At, B1); PG8_BAR; PG8_SCHED;
.LBB0_1692:
	ds_read_b128 v[144:147], v159
	ds_read_b128 v[148:151], v159 offset:1024
	ds_read_b128 v[152:155], v159 offset:2048
	ds_read_b128 v[162:165], v159 offset:3072
	ds_read_b128 v[166:169], v160
	ds_read_b128 v[170:173], v160 offset:1024
	ds_read_b128 v[174:177], v160 offset:2048
	ds_read_b128 v[178:181], v160 offset:3072
	s_add_u32 s6, s50, 0x100
	s_addc_u32 s7, s51, 0
	s_cmp_eq_u32 s58, 12
	s_cselect_b32 s55, s47, s7
	s_cselect_b32 s54, s46, s6
	s_cselect_b32 s53, s21, s57
	s_cselect_b32 s52, s38, s45
	s_add_i32 m0, s0, 0xc000
	ds_read_b128 v[182:185], v161
	global_load_lds_dwordx4 v136, s[50:51]
	s_add_i32 m0, s0, 0xe000
	ds_read_b128 v[186:189], v161 offset:1024
	global_load_lds_dwordx4 v138, s[50:51]
	ds_read_b128 v[190:193], v161 offset:2048
	ds_read_b128 v[194:197], v161 offset:3072
	ds_read_b128 v[198:201], v161 offset:4096
	ds_read_b128 v[202:205], v161 offset:5120
	ds_read_b128 v[206:209], v161 offset:6144
	ds_read_b128 v[210:213], v161 offset:7168
	s_waitcnt vmcnt(8)
	s_waitcnt lgkmcnt(0)
	s_barrier
	s_setprio 1
	s_waitcnt lgkmcnt(0)
	v_mfma_f32_16x16x32_bf16 v[124:127], v[144:147], v[182:185], v[124:127]
	v_mfma_f32_16x16x32_bf16 v[120:123], v[152:155], v[182:185], v[120:123]
	v_mfma_f32_16x16x32_bf16 v[116:119], v[144:147], v[190:193], v[116:119]
	v_mfma_f32_16x16x32_bf16 v[112:115], v[152:155], v[190:193], v[112:115]
	v_mfma_f32_16x16x32_bf16 v[108:111], v[144:147], v[198:201], v[108:111]
	v_mfma_f32_16x16x32_bf16 v[104:107], v[152:155], v[198:201], v[104:107]
	v_mfma_f32_16x16x32_bf16 v[100:103], v[144:147], v[206:209], v[100:103]
	v_mfma_f32_16x16x32_bf16 v[96:99], v[152:155], v[206:209], v[96:99]
	v_mfma_f32_16x16x32_bf16 v[124:127], v[148:151], v[186:189], v[124:127]
	v_mfma_f32_16x16x32_bf16 v[120:123], v[162:165], v[186:189], v[120:123]
	v_mfma_f32_16x16x32_bf16 v[116:119], v[148:151], v[194:197], v[116:119]
	v_mfma_f32_16x16x32_bf16 v[112:115], v[162:165], v[194:197], v[112:115]
	v_mfma_f32_16x16x32_bf16 v[108:111], v[148:151], v[202:205], v[108:111]
	v_mfma_f32_16x16x32_bf16 v[104:107], v[162:165], v[202:205], v[104:107]
	v_mfma_f32_16x16x32_bf16 v[100:103], v[148:151], v[210:213], v[100:103]
	v_mfma_f32_16x16x32_bf16 v[96:99], v[162:165], v[210:213], v[96:99]
	s_setprio 0
	s_setprio 1
	v_mfma_f32_16x16x32_bf16 v[60:63], v[166:169], v[182:185], v[60:63]
	v_mfma_f32_16x16x32_bf16 v[56:59], v[174:177], v[182:185], v[56:59]
	v_mfma_f32_16x16x32_bf16 v[52:55], v[166:169], v[190:193], v[52:55]
	v_mfma_f32_16x16x32_bf16 v[48:51], v[174:177], v[190:193], v[48:51]
	v_mfma_f32_16x16x32_bf16 v[44:47], v[166:169], v[198:201], v[44:47]
	v_mfma_f32_16x16x32_bf16 v[40:43], v[174:177], v[198:201], v[40:43]
	v_mfma_f32_16x16x32_bf16 v[36:39], v[166:169], v[206:209], v[36:39]
	v_mfma_f32_16x16x32_bf16 v[32:35], v[174:177], v[206:209], v[32:35]
	v_mfma_f32_16x16x32_bf16 v[60:63], v[170:173], v[186:189], v[60:63]
	v_mfma_f32_16x16x32_bf16 v[56:59], v[178:181], v[186:189], v[56:59]
	v_mfma_f32_16x16x32_bf16 v[52:55], v[170:173], v[194:197], v[52:55]
	v_mfma_f32_16x16x32_bf16 v[48:51], v[178:181], v[194:197], v[48:51]
	v_mfma_f32_16x16x32_bf16 v[44:47], v[170:173], v[202:205], v[44:47]
	v_mfma_f32_16x16x32_bf16 v[40:43], v[178:181], v[202:205], v[40:43]
	v_mfma_f32_16x16x32_bf16 v[36:39], v[170:173], v[210:213], v[36:39]
	v_mfma_f32_16x16x32_bf16 v[32:35], v[178:181], v[210:213], v[32:35]
	s_setprio 0
	s_barrier
	s_add_i32 s24, s34, s94
	s_mov_b32 m0, s24
	ds_read_b128 v[182:185], v161 offset:16384
	global_load_lds_dwordx4 v132, s[52:53]
	s_add_i32 m0, s24, 0x2000
	s_add_u32 s24, s52, 0x40000
	s_addc_u32 s25, s53, 0
	s_add_i32 s50, s35, s94
	global_load_lds_dwordx4 v128, s[52:53]
	s_mov_b32 m0, s50
	ds_read_b128 v[186:189], v161 offset:17408
	global_load_lds_dwordx4 v132, s[24:25]
	s_add_i32 m0, s50, 0x2000
	ds_read_b128 v[190:193], v161 offset:18432
	global_load_lds_dwordx4 v128, s[24:25]
	s_mov_b32 m0, s0
	ds_read_b128 v[194:197], v161 offset:19456
	global_load_lds_dwordx4 v134, s[54:55]
	s_mov_b32 m0, s1
	ds_read_b128 v[198:201], v161 offset:20480
	global_load_lds_dwordx4 v130, s[54:55]
	ds_read_b128 v[202:205], v161 offset:21504
	ds_read_b128 v[206:209], v161 offset:22528
	ds_read_b128 v[210:213], v161 offset:23552
	s_waitcnt vmcnt(8)
	s_waitcnt lgkmcnt(0)
	s_barrier
	s_setprio 1
	s_waitcnt lgkmcnt(0)
	v_mfma_f32_16x16x32_bf16 v[92:95], v[144:147], v[182:185], v[92:95]
	v_mfma_f32_16x16x32_bf16 v[88:91], v[152:155], v[182:185], v[88:91]
	v_mfma_f32_16x16x32_bf16 v[84:87], v[144:147], v[190:193], v[84:87]
	v_mfma_f32_16x16x32_bf16 v[80:83], v[152:155], v[190:193], v[80:83]
	v_mfma_f32_16x16x32_bf16 v[76:79], v[144:147], v[198:201], v[76:79]
	v_mfma_f32_16x16x32_bf16 v[72:75], v[152:155], v[198:201], v[72:75]
	v_mfma_f32_16x16x32_bf16 v[68:71], v[144:147], v[206:209], v[68:71]
	v_mfma_f32_16x16x32_bf16 v[64:67], v[152:155], v[206:209], v[64:67]
	v_mfma_f32_16x16x32_bf16 v[92:95], v[148:151], v[186:189], v[92:95]
	v_mfma_f32_16x16x32_bf16 v[88:91], v[162:165], v[186:189], v[88:91]
	v_mfma_f32_16x16x32_bf16 v[84:87], v[148:151], v[194:197], v[84:87]
	v_mfma_f32_16x16x32_bf16 v[80:83], v[162:165], v[194:197], v[80:83]
	v_mfma_f32_16x16x32_bf16 v[76:79], v[148:151], v[202:205], v[76:79]
	v_mfma_f32_16x16x32_bf16 v[72:75], v[162:165], v[202:205], v[72:75]
	v_mfma_f32_16x16x32_bf16 v[68:71], v[148:151], v[210:213], v[68:71]
	v_mfma_f32_16x16x32_bf16 v[64:67], v[162:165], v[210:213], v[64:67]
	s_setprio 0
	s_setprio 1
	v_mfma_f32_16x16x32_bf16 v[28:31], v[166:169], v[182:185], v[28:31]
	v_mfma_f32_16x16x32_bf16 v[24:27], v[174:177], v[182:185], v[24:27]
	v_mfma_f32_16x16x32_bf16 v[20:23], v[166:169], v[190:193], v[20:23]
	v_mfma_f32_16x16x32_bf16 v[16:19], v[174:177], v[190:193], v[16:19]
	v_mfma_f32_16x16x32_bf16 v[12:15], v[166:169], v[198:201], v[12:15]
	v_mfma_f32_16x16x32_bf16 v[8:11], v[174:177], v[198:201], v[8:11]
	v_mfma_f32_16x16x32_bf16 v[4:7], v[166:169], v[206:209], v[4:7]
	v_mfma_f32_16x16x32_bf16 v[0:3], v[174:177], v[206:209], v[0:3]
	v_mfma_f32_16x16x32_bf16 v[28:31], v[170:173], v[186:189], v[28:31]
	v_mfma_f32_16x16x32_bf16 v[24:27], v[178:181], v[186:189], v[24:27]
	v_mfma_f32_16x16x32_bf16 v[20:23], v[170:173], v[194:197], v[20:23]
	v_mfma_f32_16x16x32_bf16 v[16:19], v[178:181], v[194:197], v[16:19]
	v_mfma_f32_16x16x32_bf16 v[12:15], v[170:173], v[202:205], v[12:15]
	v_mfma_f32_16x16x32_bf16 v[8:11], v[178:181], v[202:205], v[8:11]
	v_mfma_f32_16x16x32_bf16 v[4:7], v[170:173], v[210:213], v[4:7]
	v_mfma_f32_16x16x32_bf16 v[0:3], v[178:181], v[210:213], v[0:3]
	s_setprio 0
	s_barrier
; #define PG8_STAGE(bufoff, gbase, voff) do { _Pragma("unroll") for (int _i = 0; _i < 2; ++_i) \
;         __builtin_amdgcn_global_load_lds((const unsigned*)((const char*)(gbase) + (voff)[_i]), (LAS unsigned*)(lds + (bufoff) + ldsw + _i * 8192), 16, 0, 0); } while (0)
; #define PG8_LDA(dst, b, h) do { _Pragma("unroll") for (int m = 0; m < 4; ++m) _Pragma("unroll") for (int k = 0; k < 2; ++k) dst[m][k] = *(const LAS bf16x8*)(lds + PG8_SA(b, h) + aoff + m * 2048 + k * 1024); } while (0)
; #define PG8_LDB(dst, b, h) do { _Pragma("unroll") for (int n = 0; n < 2; ++n) _Pragma("unroll") for (int k = 0; k < 2; ++k) dst[n][k] = *(const LAS bf16x8*)(lds + PG8_SB(b, h) + boff + n * 2048 + k * 1024); } while (0)
; #define PG8_MMA(ai, bj, At, Bt) do { __builtin_amdgcn_s_setprio(1); _Pragma("unroll") for (int m = 0; m < 4; ++m) _Pragma("unroll") for (int n = 0; n < 2; ++n) _Pragma("unroll") for (int k = 0; k < 2; ++k) \
;         acc[ai][bj][m][n] = __builtin_amdgcn_mfma_f32_16x16x32_bf16(Bt[n][k], At[m][k], acc[ai][bj][m][n], 0, 0, 0); __builtin_amdgcn_s_setprio(0); } while (0)
; #define PG8_WAIT_V(n) asm volatile("s_waitcnt vmcnt(" #n ")" ::: "memory")
; #define PG8_WAIT_L(n) asm volatile("s_waitcnt lgkmcnt(" #n ")" ::: "memory")
; #define PG8_BAR __builtin_amdgcn_s_barrier()
; #define PG8_SCHED __builtin_amdgcn_sched_barrier(0)
; template <class Epi>
; __device__ __forceinline__ void gemm_phase(LAS unsigned char* lds, const Gemm g, const StaticOrder& S, const Epi& E, const int wid) {
;     ...
;             PG8_LDB(B0, 1, 0); PG8_LDB(B1, 1, 1); PG8_SCHED; PG8_LDA(At, 1, 0); PG8_STAGE(PG8_SA(0, 1), a2 + hstepA, voffA);
;             PG8_WAIT_V(8); PG8_WAIT_L(0); PG8_BAR; PG8_MMA(0, 0, At, B0); PG8_MMA(0, 1, At, B1); PG8_BAR; PG8_SCHED;
;             PG8_LDA(At, 1, 1); PG8_STAGE(PG8_SB(1, 0), b3, voffB); PG8_STAGE(PG8_SB(1, 1), b3 + hstepB, voffB); PG8_STAGE(PG8_SA(1, 0), a3, voffA);
;             PG8_WAIT_V(8); PG8_WAIT_L(0); PG8_BAR; PG8_MMA(1, 0, At, B0); PG8_MMA(1, 1, At, B1); PG8_BAR; PG8_SCHED;
;         }
	s_add_i32 s50, 0, 0x18000
	s_add_i32 s51, 0, 0x1c000
	v_add_u32_e32 v162, s50, v156
	v_add_u32_e32 v178, s51, v156
	ds_read_b128 v[144:147], v162
	ds_read_b128 v[148:151], v162 offset:1024
	ds_read_b128 v[152:155], v162 offset:2048
	ds_read_b128 v[162:165], v162 offset:3072
	ds_read_b128 v[166:169], v178
	ds_read_b128 v[170:173], v178 offset:1024
	ds_read_b128 v[174:177], v178 offset:2048
	ds_read_b128 v[178:181], v178 offset:3072
	s_add_u32 s24, s54, 0x40000
	s_addc_u32 s25, s55, 0
	s_mov_b32 m0, s15
	ds_read_b128 v[182:185], v161 offset:32768
	global_load_lds_dwordx4 v134, s[24:25]
	s_mov_b32 m0, s26
	ds_read_b128 v[186:189], v161 offset:33792
	global_load_lds_dwordx4 v130, s[24:25]
	ds_read_b128 v[190:193], v161 offset:34816
	ds_read_b128 v[194:197], v161 offset:35840
	ds_read_b128 v[198:201], v161 offset:36864
	ds_read_b128 v[202:205], v161 offset:37888
	ds_read_b128 v[206:209], v161 offset:38912
	ds_read_b128 v[210:213], v161 offset:39936
	s_waitcnt vmcnt(8)
	s_waitcnt lgkmcnt(0)
	s_barrier
	s_setprio 1
	s_waitcnt lgkmcnt(0)
	v_mfma_f32_16x16x32_bf16 v[124:127], v[144:147], v[182:185], v[124:127]
	v_mfma_f32_16x16x32_bf16 v[120:123], v[152:155], v[182:185], v[120:123]
	v_mfma_f32_16x16x32_bf16 v[116:119], v[144:147], v[190:193], v[116:119]
	v_mfma_f32_16x16x32_bf16 v[112:115], v[152:155], v[190:193], v[112:115]
	v_mfma_f32_16x16x32_bf16 v[108:111], v[144:147], v[198:201], v[108:111]
	v_mfma_f32_16x16x32_bf16 v[104:107], v[152:155], v[198:201], v[104:107]
	v_mfma_f32_16x16x32_bf16 v[100:103], v[144:147], v[206:209], v[100:103]
	v_mfma_f32_16x16x32_bf16 v[96:99], v[152:155], v[206:209], v[96:99]
	v_mfma_f32_16x16x32_bf16 v[124:127], v[148:151], v[186:189], v[124:127]
	v_mfma_f32_16x16x32_bf16 v[120:123], v[162:165], v[186:189], v[120:123]
	v_mfma_f32_16x16x32_bf16 v[116:119], v[148:151], v[194:197], v[116:119]
	v_mfma_f32_16x16x32_bf16 v[112:115], v[162:165], v[194:197], v[112:115]
	v_mfma_f32_16x16x32_bf16 v[108:111], v[148:151], v[202:205], v[108:111]
	v_mfma_f32_16x16x32_bf16 v[104:107], v[162:165], v[202:205], v[104:107]
	v_mfma_f32_16x16x32_bf16 v[100:103], v[148:151], v[210:213], v[100:103]
	v_mfma_f32_16x16x32_bf16 v[96:99], v[162:165], v[210:213], v[96:99]
	s_setprio 0
	s_setprio 1
	v_mfma_f32_16x16x32_bf16 v[60:63], v[166:169], v[182:185], v[60:63]
	v_mfma_f32_16x16x32_bf16 v[56:59], v[174:177], v[182:185], v[56:59]
	v_mfma_f32_16x16x32_bf16 v[52:55], v[166:169], v[190:193], v[52:55]
	v_mfma_f32_16x16x32_bf16 v[48:51], v[174:177], v[190:193], v[48:51]
	v_mfma_f32_16x16x32_bf16 v[44:47], v[166:169], v[198:201], v[44:47]
	v_mfma_f32_16x16x32_bf16 v[40:43], v[174:177], v[198:201], v[40:43]
	v_mfma_f32_16x16x32_bf16 v[36:39], v[166:169], v[206:209], v[36:39]
	v_mfma_f32_16x16x32_bf16 v[32:35], v[174:177], v[206:209], v[32:35]
	v_mfma_f32_16x16x32_bf16 v[60:63], v[170:173], v[186:189], v[60:63]
	v_mfma_f32_16x16x32_bf16 v[56:59], v[178:181], v[186:189], v[56:59]
	v_mfma_f32_16x16x32_bf16 v[52:55], v[170:173], v[194:197], v[52:55]
	v_mfma_f32_16x16x32_bf16 v[48:51], v[178:181], v[194:197], v[48:51]
	v_mfma_f32_16x16x32_bf16 v[44:47], v[170:173], v[202:205], v[44:47]
	v_mfma_f32_16x16x32_bf16 v[40:43], v[178:181], v[202:205], v[40:43]
	v_mfma_f32_16x16x32_bf16 v[36:39], v[170:173], v[210:213], v[36:39]
	v_mfma_f32_16x16x32_bf16 v[32:35], v[178:181], v[210:213], v[32:35]
	s_setprio 0
	s_barrier
	s_add_i32 s24, s50, s94
	s_add_u32 s98, s52, 0x80
	s_addc_u32 s99, s53, 0
	s_mov_b32 m0, s24
	ds_read_b128 v[182:185], v161 offset:49152
	global_load_lds_dwordx4 v132, s[98:99]
	s_add_i32 m0, s24, 0x2000
	s_add_u32 s24, s52, 0x40080
	s_addc_u32 s25, s53, 0
	s_add_i32 s50, s51, s94
	global_load_lds_dwordx4 v128, s[98:99]
	s_mov_b32 m0, s50
	ds_read_b128 v[186:189], v161 offset:50176
	global_load_lds_dwordx4 v132, s[24:25]
	s_add_i32 m0, s50, 0x2000
	ds_read_b128 v[190:193], v161 offset:51200
	global_load_lds_dwordx4 v128, s[24:25]
	s_add_u32 s100, s54, 0x80
	s_addc_u32 s101, s55, 0
	s_mov_b32 m0, s28
	ds_read_b128 v[194:197], v161 offset:52224
	global_load_lds_dwordx4 v134, s[100:101]
	s_mov_b32 m0, s29
	ds_read_b128 v[198:201], v161 offset:53248
	global_load_lds_dwordx4 v130, s[100:101]
	ds_read_b128 v[202:205], v161 offset:54272
	ds_read_b128 v[206:209], v161 offset:55296
	ds_read_b128 v[210:213], v161 offset:56320
	s_waitcnt vmcnt(8)
	s_waitcnt lgkmcnt(0)
	s_barrier
	s_setprio 1
	s_waitcnt lgkmcnt(0)
	v_mfma_f32_16x16x32_bf16 v[92:95], v[144:147], v[182:185], v[92:95]
	v_mfma_f32_16x16x32_bf16 v[88:91], v[152:155], v[182:185], v[88:91]
	v_mfma_f32_16x16x32_bf16 v[84:87], v[144:147], v[190:193], v[84:87]
	v_mfma_f32_16x16x32_bf16 v[80:83], v[152:155], v[190:193], v[80:83]
	v_mfma_f32_16x16x32_bf16 v[76:79], v[144:147], v[198:201], v[76:79]
	v_mfma_f32_16x16x32_bf16 v[72:75], v[152:155], v[198:201], v[72:75]
	v_mfma_f32_16x16x32_bf16 v[68:71], v[144:147], v[206:209], v[68:71]
	v_mfma_f32_16x16x32_bf16 v[64:67], v[152:155], v[206:209], v[64:67]
	v_mfma_f32_16x16x32_bf16 v[92:95], v[148:151], v[186:189], v[92:95]
	v_mfma_f32_16x16x32_bf16 v[88:91], v[162:165], v[186:189], v[88:91]
	v_mfma_f32_16x16x32_bf16 v[84:87], v[148:151], v[194:197], v[84:87]
	v_mfma_f32_16x16x32_bf16 v[80:83], v[162:165], v[194:197], v[80:83]
	v_mfma_f32_16x16x32_bf16 v[76:79], v[148:151], v[202:205], v[76:79]
	v_mfma_f32_16x16x32_bf16 v[72:75], v[162:165], v[202:205], v[72:75]
	v_mfma_f32_16x16x32_bf16 v[68:71], v[148:151], v[210:213], v[68:71]
	v_mfma_f32_16x16x32_bf16 v[64:67], v[162:165], v[210:213], v[64:67]
	s_setprio 0
	s_setprio 1
	v_mfma_f32_16x16x32_bf16 v[28:31], v[166:169], v[182:185], v[28:31]
	v_mfma_f32_16x16x32_bf16 v[24:27], v[174:177], v[182:185], v[24:27]
	v_mfma_f32_16x16x32_bf16 v[20:23], v[166:169], v[190:193], v[20:23]
	v_mfma_f32_16x16x32_bf16 v[16:19], v[174:177], v[190:193], v[16:19]
	v_mfma_f32_16x16x32_bf16 v[12:15], v[166:169], v[198:201], v[12:15]
	v_mfma_f32_16x16x32_bf16 v[8:11], v[174:177], v[198:201], v[8:11]
	v_mfma_f32_16x16x32_bf16 v[4:7], v[166:169], v[206:209], v[4:7]
	v_mfma_f32_16x16x32_bf16 v[0:3], v[174:177], v[206:209], v[0:3]
	v_mfma_f32_16x16x32_bf16 v[28:31], v[170:173], v[186:189], v[28:31]
	v_mfma_f32_16x16x32_bf16 v[24:27], v[178:181], v[186:189], v[24:27]
	v_mfma_f32_16x16x32_bf16 v[20:23], v[170:173], v[194:197], v[20:23]
	v_mfma_f32_16x16x32_bf16 v[16:19], v[178:181], v[194:197], v[16:19]
	v_mfma_f32_16x16x32_bf16 v[12:15], v[170:173], v[202:205], v[12:15]
	v_mfma_f32_16x16x32_bf16 v[8:11], v[178:181], v[202:205], v[8:11]
	v_mfma_f32_16x16x32_bf16 v[4:7], v[170:173], v[210:213], v[4:7]
	v_mfma_f32_16x16x32_bf16 v[0:3], v[178:181], v[210:213], v[0:3]
	s_setprio 0
	s_barrier
	s_add_i32 s58, s58, 2
	s_add_u32 s45, s45, 0x100
	s_addc_u32 s57, s57, 0
	s_cmp_gt_u32 s58, 13
	s_mov_b64 s[50:51], s[6:7]
	s_cbranch_scc0 .LBB0_1692
	s_and_b64 vcc, exec, s[22:23]
	s_cbranch_vccz .LBB0_1695
	s_barrier

; #define PG8_STAGE(bufoff, gbase, voff) do { _Pragma("unroll") for (int _i = 0; _i < 2; ++_i) \
;         __builtin_amdgcn_global_load_lds((const unsigned*)((const char*)(gbase) + (voff)[_i]), (LAS unsigned*)(lds + (bufoff) + ldsw + _i * 8192), 16, 0, 0); } while (0)
; #define PG8_LDA(dst, b, h) do { _Pragma("unroll") for (int m = 0; m < 4; ++m) _Pragma("unroll") for (int k = 0; k < 2; ++k) dst[m][k] = *(const LAS bf16x8*)(lds + PG8_SA(b, h) + aoff + m * 2048 + k * 1024); } while (0)
; #define PG8_LDB(dst, b, h) do { _Pragma("unroll") for (int n = 0; n < 2; ++n) _Pragma("unroll") for (int k = 0; k < 2; ++k) dst[n][k] = *(const LAS bf16x8*)(lds + PG8_SB(b, h) + boff + n * 2048 + k * 1024); } while (0)
; #define PG8_MMA(ai, bj, At, Bt) do { __builtin_amdgcn_s_setprio(1); _Pragma("unroll") for (int m = 0; m < 4; ++m) _Pragma("unroll") for (int n = 0; n < 2; ++n) _Pragma("unroll") for (int k = 0; k < 2; ++k) \
;         acc[ai][bj][m][n] = __builtin_amdgcn_mfma_f32_16x16x32_bf16(Bt[n][k], At[m][k], acc[ai][bj][m][n], 0, 0, 0); __builtin_amdgcn_s_setprio(0); } while (0)
; #define PG8_WAIT_V(n) asm volatile("s_waitcnt vmcnt(" #n ")" ::: "memory")
; #define PG8_WAIT_L(n) asm volatile("s_waitcnt lgkmcnt(" #n ")" ::: "memory")
; #define PG8_BAR __builtin_amdgcn_s_barrier()
; #define PG8_SCHED __builtin_amdgcn_sched_barrier(0)
; template <class Epi>
; __device__ __forceinline__ void gemm_phase(LAS unsigned char* lds, const Gemm g, const StaticOrder& S, const Epi& E, const int wid) {
;     ...
;             PG8_LDB(B0, 0, 0); PG8_LDB(B1, 0, 1); PG8_SCHED; PG8_LDA(At, 0, 0); PG8_STAGE(PG8_SA(1, 1), a1 + hstepA, voffA);
;             PG8_WAIT_V(8); PG8_WAIT_L(0); PG8_BAR; PG8_MMA(0, 0, At, B0); PG8_MMA(0, 1, At, B1); PG8_BAR; PG8_SCHED;
;             PG8_LDA(At, 0, 1); PG8_STAGE(PG8_SB(0, 0), b2, voffB); PG8_STAGE(PG8_SB(0, 1), b2 + hstepB, voffB); PG8_STAGE(PG8_SA(0, 0), a2, voffA);
;             PG8_WAIT_V(8); PG8_WAIT_L(0); PG8_BAR; PG8_MMA(1, 0, At, B0); PG8_MMA(1, 1, At, B1); PG8_BAR; PG8_SCHED;
.LBB0_1727:
	ds_read_b128 v[144:147], v157
	ds_read_b128 v[148:151], v157 offset:1024
	ds_read_b128 v[160:163], v157 offset:2048
	ds_read_b128 v[164:167], v157 offset:3072
	ds_read_b128 v[168:171], v158
	ds_read_b128 v[172:175], v158 offset:1024
	ds_read_b128 v[176:179], v158 offset:2048
	ds_read_b128 v[180:183], v158 offset:3072
	s_add_u32 s6, s46, 0x100
	s_addc_u32 s7, s47, 0
	s_cmp_eq_u32 s54, 28
	s_cselect_b32 s51, s43, s7
	s_cselect_b32 s50, s42, s6
	s_cselect_b32 s49, s21, s53
	s_cselect_b32 s48, s41, s52
	s_add_i32 m0, s1, 0xc000
	ds_read_b128 v[184:187], v159
	global_load_lds_dwordx4 v136, s[46:47]
	s_add_i32 m0, s1, 0xe000
	ds_read_b128 v[188:191], v159 offset:1024
	global_load_lds_dwordx4 v138, s[46:47]
	ds_read_b128 v[192:195], v159 offset:2048
	ds_read_b128 v[196:199], v159 offset:3072
	ds_read_b128 v[200:203], v159 offset:4096
	ds_read_b128 v[204:207], v159 offset:5120
	ds_read_b128 v[208:211], v159 offset:6144
	ds_read_b128 v[212:215], v159 offset:7168
	s_waitcnt vmcnt(8)
	s_waitcnt lgkmcnt(0)
	s_barrier
	s_setprio 1
	s_waitcnt lgkmcnt(0)
	v_mfma_f32_16x16x32_bf16 v[124:127], v[144:147], v[184:187], v[124:127]
	v_mfma_f32_16x16x32_bf16 v[120:123], v[160:163], v[184:187], v[120:123]
	v_mfma_f32_16x16x32_bf16 v[116:119], v[144:147], v[192:195], v[116:119]
	v_mfma_f32_16x16x32_bf16 v[112:115], v[160:163], v[192:195], v[112:115]
	v_mfma_f32_16x16x32_bf16 v[108:111], v[144:147], v[200:203], v[108:111]
	v_mfma_f32_16x16x32_bf16 v[104:107], v[160:163], v[200:203], v[104:107]
	v_mfma_f32_16x16x32_bf16 v[100:103], v[144:147], v[208:211], v[100:103]
	v_mfma_f32_16x16x32_bf16 v[96:99], v[160:163], v[208:211], v[96:99]
	v_mfma_f32_16x16x32_bf16 v[124:127], v[148:151], v[188:191], v[124:127]
	v_mfma_f32_16x16x32_bf16 v[120:123], v[164:167], v[188:191], v[120:123]
	v_mfma_f32_16x16x32_bf16 v[116:119], v[148:151], v[196:199], v[116:119]
	v_mfma_f32_16x16x32_bf16 v[112:115], v[164:167], v[196:199], v[112:115]
	v_mfma_f32_16x16x32_bf16 v[108:111], v[148:151], v[204:207], v[108:111]
	v_mfma_f32_16x16x32_bf16 v[104:107], v[164:167], v[204:207], v[104:107]
	v_mfma_f32_16x16x32_bf16 v[100:103], v[148:151], v[212:215], v[100:103]
	v_mfma_f32_16x16x32_bf16 v[96:99], v[164:167], v[212:215], v[96:99]
	s_setprio 0
	s_setprio 1
	v_mfma_f32_16x16x32_bf16 v[76:79], v[168:171], v[184:187], v[76:79]
	v_mfma_f32_16x16x32_bf16 v[64:67], v[176:179], v[184:187], v[64:67]
	v_mfma_f32_16x16x32_bf16 v[56:59], v[168:171], v[192:195], v[56:59]
	v_mfma_f32_16x16x32_bf16 v[48:51], v[176:179], v[192:195], v[48:51]
	v_mfma_f32_16x16x32_bf16 v[44:47], v[168:171], v[200:203], v[44:47]
	v_mfma_f32_16x16x32_bf16 v[40:43], v[176:179], v[200:203], v[40:43]
	v_mfma_f32_16x16x32_bf16 v[36:39], v[168:171], v[208:211], v[36:39]
	v_mfma_f32_16x16x32_bf16 v[32:35], v[176:179], v[208:211], v[32:35]
	v_mfma_f32_16x16x32_bf16 v[76:79], v[172:175], v[188:191], v[76:79]
	v_mfma_f32_16x16x32_bf16 v[64:67], v[180:183], v[188:191], v[64:67]
	v_mfma_f32_16x16x32_bf16 v[56:59], v[172:175], v[196:199], v[56:59]
	v_mfma_f32_16x16x32_bf16 v[48:51], v[180:183], v[196:199], v[48:51]
	v_mfma_f32_16x16x32_bf16 v[44:47], v[172:175], v[204:207], v[44:47]
	v_mfma_f32_16x16x32_bf16 v[40:43], v[180:183], v[204:207], v[40:43]
	v_mfma_f32_16x16x32_bf16 v[36:39], v[172:175], v[212:215], v[36:39]
	v_mfma_f32_16x16x32_bf16 v[32:35], v[180:183], v[212:215], v[32:35]
	s_setprio 0
	s_barrier
	s_add_i32 s24, s35, s94
	s_mov_b32 m0, s24
	ds_read_b128 v[184:187], v159 offset:16384
	global_load_lds_dwordx4 v132, s[48:49]
	s_add_i32 m0, s24, 0x2000
	s_add_u32 s24, s48, 0x80000
	s_addc_u32 s25, s49, 0
	s_add_i32 s46, s36, s94
	global_load_lds_dwordx4 v128, s[48:49]
	s_mov_b32 m0, s46
	ds_read_b128 v[188:191], v159 offset:17408
	global_load_lds_dwordx4 v132, s[24:25]
	s_add_i32 m0, s46, 0x2000
	ds_read_b128 v[192:195], v159 offset:18432
	global_load_lds_dwordx4 v128, s[24:25]
	s_mov_b32 m0, s1
	ds_read_b128 v[196:199], v159 offset:19456
	global_load_lds_dwordx4 v134, s[50:51]
	s_mov_b32 m0, s15
	ds_read_b128 v[200:203], v159 offset:20480
	global_load_lds_dwordx4 v130, s[50:51]
	ds_read_b128 v[204:207], v159 offset:21504
	ds_read_b128 v[208:211], v159 offset:22528
	ds_read_b128 v[212:215], v159 offset:23552
	s_waitcnt vmcnt(8)
	s_waitcnt lgkmcnt(0)
	s_barrier
	s_setprio 1
	s_waitcnt lgkmcnt(0)
	v_mfma_f32_16x16x32_bf16 v[92:95], v[144:147], v[184:187], v[92:95]
	v_mfma_f32_16x16x32_bf16 v[88:91], v[160:163], v[184:187], v[88:91]
	v_mfma_f32_16x16x32_bf16 v[84:87], v[144:147], v[192:195], v[84:87]
	v_mfma_f32_16x16x32_bf16 v[80:83], v[160:163], v[192:195], v[80:83]
	v_mfma_f32_16x16x32_bf16 v[72:75], v[144:147], v[200:203], v[72:75]
	v_mfma_f32_16x16x32_bf16 v[68:71], v[160:163], v[200:203], v[68:71]
	v_mfma_f32_16x16x32_bf16 v[60:63], v[144:147], v[208:211], v[60:63]
	v_mfma_f32_16x16x32_bf16 v[52:55], v[160:163], v[208:211], v[52:55]
	v_mfma_f32_16x16x32_bf16 v[92:95], v[148:151], v[188:191], v[92:95]
	v_mfma_f32_16x16x32_bf16 v[88:91], v[164:167], v[188:191], v[88:91]
	v_mfma_f32_16x16x32_bf16 v[84:87], v[148:151], v[196:199], v[84:87]
	v_mfma_f32_16x16x32_bf16 v[80:83], v[164:167], v[196:199], v[80:83]
	v_mfma_f32_16x16x32_bf16 v[72:75], v[148:151], v[204:207], v[72:75]
	v_mfma_f32_16x16x32_bf16 v[68:71], v[164:167], v[204:207], v[68:71]
	v_mfma_f32_16x16x32_bf16 v[60:63], v[148:151], v[212:215], v[60:63]
	v_mfma_f32_16x16x32_bf16 v[52:55], v[164:167], v[212:215], v[52:55]
	s_setprio 0
	s_setprio 1
	v_mfma_f32_16x16x32_bf16 v[28:31], v[168:171], v[184:187], v[28:31]
	v_mfma_f32_16x16x32_bf16 v[24:27], v[176:179], v[184:187], v[24:27]
	v_mfma_f32_16x16x32_bf16 v[20:23], v[168:171], v[192:195], v[20:23]
	v_mfma_f32_16x16x32_bf16 v[16:19], v[176:179], v[192:195], v[16:19]
	v_mfma_f32_16x16x32_bf16 v[12:15], v[168:171], v[200:203], v[12:15]
	v_mfma_f32_16x16x32_bf16 v[8:11], v[176:179], v[200:203], v[8:11]
	v_mfma_f32_16x16x32_bf16 v[4:7], v[168:171], v[208:211], v[4:7]
	v_mfma_f32_16x16x32_bf16 v[0:3], v[176:179], v[208:211], v[0:3]
	v_mfma_f32_16x16x32_bf16 v[28:31], v[172:175], v[188:191], v[28:31]
	v_mfma_f32_16x16x32_bf16 v[24:27], v[180:183], v[188:191], v[24:27]
	v_mfma_f32_16x16x32_bf16 v[20:23], v[172:175], v[196:199], v[20:23]
	v_mfma_f32_16x16x32_bf16 v[16:19], v[180:183], v[196:199], v[16:19]
	v_mfma_f32_16x16x32_bf16 v[12:15], v[172:175], v[204:207], v[12:15]
	v_mfma_f32_16x16x32_bf16 v[8:11], v[180:183], v[204:207], v[8:11]
	v_mfma_f32_16x16x32_bf16 v[4:7], v[172:175], v[212:215], v[4:7]
	v_mfma_f32_16x16x32_bf16 v[0:3], v[180:183], v[212:215], v[0:3]
	s_setprio 0
	s_barrier
; #define PG8_STAGE(bufoff, gbase, voff) do { _Pragma("unroll") for (int _i = 0; _i < 2; ++_i) \
;         __builtin_amdgcn_global_load_lds((const unsigned*)((const char*)(gbase) + (voff)[_i]), (LAS unsigned*)(lds + (bufoff) + ldsw + _i * 8192), 16, 0, 0); } while (0)
; #define PG8_LDA(dst, b, h) do { _Pragma("unroll") for (int m = 0; m < 4; ++m) _Pragma("unroll") for (int k = 0; k < 2; ++k) dst[m][k] = *(const LAS bf16x8*)(lds + PG8_SA(b, h) + aoff + m * 2048 + k * 1024); } while (0)
; #define PG8_LDB(dst, b, h) do { _Pragma("unroll") for (int n = 0; n < 2; ++n) _Pragma("unroll") for (int k = 0; k < 2; ++k) dst[n][k] = *(const LAS bf16x8*)(lds + PG8_SB(b, h) + boff + n * 2048 + k * 1024); } while (0)
; #define PG8_MMA(ai, bj, At, Bt) do { __builtin_amdgcn_s_setprio(1); _Pragma("unroll") for (int m = 0; m < 4; ++m) _Pragma("unroll") for (int n = 0; n < 2; ++n) _Pragma("unroll") for (int k = 0; k < 2; ++k) \
;         acc[ai][bj][m][n] = __builtin_amdgcn_mfma_f32_16x16x32_bf16(Bt[n][k], At[m][k], acc[ai][bj][m][n], 0, 0, 0); __builtin_amdgcn_s_setprio(0); } while (0)
; #define PG8_WAIT_V(n) asm volatile("s_waitcnt vmcnt(" #n ")" ::: "memory")
; #define PG8_WAIT_L(n) asm volatile("s_waitcnt lgkmcnt(" #n ")" ::: "memory")
; #define PG8_BAR __builtin_amdgcn_s_barrier()
; #define PG8_SCHED __builtin_amdgcn_sched_barrier(0)
; template <class Epi>
; __device__ __forceinline__ void gemm_phase(LAS unsigned char* lds, const Gemm g, const StaticOrder& S, const Epi& E, const int wid) {
;     ...
;             PG8_LDB(B0, 1, 0); PG8_LDB(B1, 1, 1); PG8_SCHED; PG8_LDA(At, 1, 0); PG8_STAGE(PG8_SA(0, 1), a2 + hstepA, voffA);
;             PG8_WAIT_V(8); PG8_WAIT_L(0); PG8_BAR; PG8_MMA(0, 0, At, B0); PG8_MMA(0, 1, At, B1); PG8_BAR; PG8_SCHED;
;             PG8_LDA(At, 1, 1); PG8_STAGE(PG8_SB(1, 0), b3, voffB); PG8_STAGE(PG8_SB(1, 1), b3 + hstepB, voffB); PG8_STAGE(PG8_SA(1, 0), a3, voffA);
;             PG8_WAIT_V(8); PG8_WAIT_L(0); PG8_BAR; PG8_MMA(1, 0, At, B0); PG8_MMA(1, 1, At, B1); PG8_BAR; PG8_SCHED;
;         }
	s_add_i32 s46, 0, 0x18000
	s_add_i32 s47, 0, 0x1c000
	v_add_u32_e32 v164, s46, v154
	v_add_u32_e32 v180, s47, v154
	ds_read_b128 v[144:147], v164
	ds_read_b128 v[148:151], v164 offset:1024
	ds_read_b128 v[160:163], v164 offset:2048
	ds_read_b128 v[164:167], v164 offset:3072
	ds_read_b128 v[168:171], v180
	ds_read_b128 v[172:175], v180 offset:1024
	ds_read_b128 v[176:179], v180 offset:2048
	ds_read_b128 v[180:183], v180 offset:3072
	s_add_u32 s24, s50, 0x80000
	s_addc_u32 s25, s51, 0
	s_mov_b32 m0, s26
	ds_read_b128 v[184:187], v159 offset:32768
	global_load_lds_dwordx4 v134, s[24:25]
	s_mov_b32 m0, s27
	ds_read_b128 v[188:191], v159 offset:33792
	global_load_lds_dwordx4 v130, s[24:25]
	ds_read_b128 v[192:195], v159 offset:34816
	ds_read_b128 v[196:199], v159 offset:35840
	ds_read_b128 v[200:203], v159 offset:36864
	ds_read_b128 v[204:207], v159 offset:37888
	ds_read_b128 v[208:211], v159 offset:38912
	ds_read_b128 v[212:215], v159 offset:39936
	s_waitcnt vmcnt(8)
	s_waitcnt lgkmcnt(0)
	s_barrier
	s_setprio 1
	s_waitcnt lgkmcnt(0)
	v_mfma_f32_16x16x32_bf16 v[124:127], v[144:147], v[184:187], v[124:127]
	v_mfma_f32_16x16x32_bf16 v[120:123], v[160:163], v[184:187], v[120:123]
	v_mfma_f32_16x16x32_bf16 v[116:119], v[144:147], v[192:195], v[116:119]
	v_mfma_f32_16x16x32_bf16 v[112:115], v[160:163], v[192:195], v[112:115]
	v_mfma_f32_16x16x32_bf16 v[108:111], v[144:147], v[200:203], v[108:111]
	v_mfma_f32_16x16x32_bf16 v[104:107], v[160:163], v[200:203], v[104:107]
	v_mfma_f32_16x16x32_bf16 v[100:103], v[144:147], v[208:211], v[100:103]
	v_mfma_f32_16x16x32_bf16 v[96:99], v[160:163], v[208:211], v[96:99]
	v_mfma_f32_16x16x32_bf16 v[124:127], v[148:151], v[188:191], v[124:127]
	v_mfma_f32_16x16x32_bf16 v[120:123], v[164:167], v[188:191], v[120:123]
	v_mfma_f32_16x16x32_bf16 v[116:119], v[148:151], v[196:199], v[116:119]
	v_mfma_f32_16x16x32_bf16 v[112:115], v[164:167], v[196:199], v[112:115]
	v_mfma_f32_16x16x32_bf16 v[108:111], v[148:151], v[204:207], v[108:111]
	v_mfma_f32_16x16x32_bf16 v[104:107], v[164:167], v[204:207], v[104:107]
	v_mfma_f32_16x16x32_bf16 v[100:103], v[148:151], v[212:215], v[100:103]
	v_mfma_f32_16x16x32_bf16 v[96:99], v[164:167], v[212:215], v[96:99]
	s_setprio 0
	s_setprio 1
	v_mfma_f32_16x16x32_bf16 v[76:79], v[168:171], v[184:187], v[76:79]
	v_mfma_f32_16x16x32_bf16 v[64:67], v[176:179], v[184:187], v[64:67]
	v_mfma_f32_16x16x32_bf16 v[56:59], v[168:171], v[192:195], v[56:59]
	v_mfma_f32_16x16x32_bf16 v[48:51], v[176:179], v[192:195], v[48:51]
	v_mfma_f32_16x16x32_bf16 v[44:47], v[168:171], v[200:203], v[44:47]
	v_mfma_f32_16x16x32_bf16 v[40:43], v[176:179], v[200:203], v[40:43]
	v_mfma_f32_16x16x32_bf16 v[36:39], v[168:171], v[208:211], v[36:39]
	v_mfma_f32_16x16x32_bf16 v[32:35], v[176:179], v[208:211], v[32:35]
	v_mfma_f32_16x16x32_bf16 v[76:79], v[172:175], v[188:191], v[76:79]
	v_mfma_f32_16x16x32_bf16 v[64:67], v[180:183], v[188:191], v[64:67]
	v_mfma_f32_16x16x32_bf16 v[56:59], v[172:175], v[196:199], v[56:59]
	v_mfma_f32_16x16x32_bf16 v[48:51], v[180:183], v[196:199], v[48:51]
	v_mfma_f32_16x16x32_bf16 v[44:47], v[172:175], v[204:207], v[44:47]
	v_mfma_f32_16x16x32_bf16 v[40:43], v[180:183], v[204:207], v[40:43]
	v_mfma_f32_16x16x32_bf16 v[36:39], v[172:175], v[212:215], v[36:39]
	v_mfma_f32_16x16x32_bf16 v[32:35], v[180:183], v[212:215], v[32:35]
	s_setprio 0
	s_barrier
	s_add_i32 s24, s46, s94
	s_add_u32 s98, s48, 0x80
	s_addc_u32 s99, s49, 0
	s_mov_b32 m0, s24
	ds_read_b128 v[184:187], v159 offset:49152
	global_load_lds_dwordx4 v132, s[98:99]
	s_add_i32 m0, s24, 0x2000
	s_add_u32 s24, s48, 0x80080
	s_addc_u32 s25, s49, 0
	s_add_i32 s46, s47, s94
	global_load_lds_dwordx4 v128, s[98:99]
	s_mov_b32 m0, s46
	ds_read_b128 v[188:191], v159 offset:50176
	global_load_lds_dwordx4 v132, s[24:25]
	s_add_i32 m0, s46, 0x2000
	ds_read_b128 v[192:195], v159 offset:51200
	global_load_lds_dwordx4 v128, s[24:25]
	s_add_u32 s100, s50, 0x80
	s_addc_u32 s101, s51, 0
	s_mov_b32 m0, s29
	ds_read_b128 v[196:199], v159 offset:52224
	global_load_lds_dwordx4 v134, s[100:101]
	s_mov_b32 m0, s34
	ds_read_b128 v[200:203], v159 offset:53248
	global_load_lds_dwordx4 v130, s[100:101]
	ds_read_b128 v[204:207], v159 offset:54272
	ds_read_b128 v[208:211], v159 offset:55296
	ds_read_b128 v[212:215], v159 offset:56320
	s_waitcnt vmcnt(8)
	s_waitcnt lgkmcnt(0)
	s_barrier
	s_setprio 1
	s_waitcnt lgkmcnt(0)
	v_mfma_f32_16x16x32_bf16 v[92:95], v[144:147], v[184:187], v[92:95]
	v_mfma_f32_16x16x32_bf16 v[88:91], v[160:163], v[184:187], v[88:91]
	v_mfma_f32_16x16x32_bf16 v[84:87], v[144:147], v[192:195], v[84:87]
	v_mfma_f32_16x16x32_bf16 v[80:83], v[160:163], v[192:195], v[80:83]
	v_mfma_f32_16x16x32_bf16 v[72:75], v[144:147], v[200:203], v[72:75]
	v_mfma_f32_16x16x32_bf16 v[68:71], v[160:163], v[200:203], v[68:71]
	v_mfma_f32_16x16x32_bf16 v[60:63], v[144:147], v[208:211], v[60:63]
	v_mfma_f32_16x16x32_bf16 v[52:55], v[160:163], v[208:211], v[52:55]
	v_mfma_f32_16x16x32_bf16 v[92:95], v[148:151], v[188:191], v[92:95]
	v_mfma_f32_16x16x32_bf16 v[88:91], v[164:167], v[188:191], v[88:91]
	v_mfma_f32_16x16x32_bf16 v[84:87], v[148:151], v[196:199], v[84:87]
	v_mfma_f32_16x16x32_bf16 v[80:83], v[164:167], v[196:199], v[80:83]
	v_mfma_f32_16x16x32_bf16 v[72:75], v[148:151], v[204:207], v[72:75]
	v_mfma_f32_16x16x32_bf16 v[68:71], v[164:167], v[204:207], v[68:71]
	v_mfma_f32_16x16x32_bf16 v[60:63], v[148:151], v[212:215], v[60:63]
	v_mfma_f32_16x16x32_bf16 v[52:55], v[164:167], v[212:215], v[52:55]
	s_setprio 0
	s_setprio 1
	v_mfma_f32_16x16x32_bf16 v[28:31], v[168:171], v[184:187], v[28:31]
	v_mfma_f32_16x16x32_bf16 v[24:27], v[176:179], v[184:187], v[24:27]
	v_mfma_f32_16x16x32_bf16 v[20:23], v[168:171], v[192:195], v[20:23]
	v_mfma_f32_16x16x32_bf16 v[16:19], v[176:179], v[192:195], v[16:19]
	v_mfma_f32_16x16x32_bf16 v[12:15], v[168:171], v[200:203], v[12:15]
	v_mfma_f32_16x16x32_bf16 v[8:11], v[176:179], v[200:203], v[8:11]
	v_mfma_f32_16x16x32_bf16 v[4:7], v[168:171], v[208:211], v[4:7]
	v_mfma_f32_16x16x32_bf16 v[0:3], v[176:179], v[208:211], v[0:3]
	v_mfma_f32_16x16x32_bf16 v[28:31], v[172:175], v[188:191], v[28:31]
	v_mfma_f32_16x16x32_bf16 v[24:27], v[180:183], v[188:191], v[24:27]
	v_mfma_f32_16x16x32_bf16 v[20:23], v[172:175], v[196:199], v[20:23]
	v_mfma_f32_16x16x32_bf16 v[16:19], v[180:183], v[196:199], v[16:19]
	v_mfma_f32_16x16x32_bf16 v[12:15], v[172:175], v[204:207], v[12:15]
	v_mfma_f32_16x16x32_bf16 v[8:11], v[180:183], v[204:207], v[8:11]
	v_mfma_f32_16x16x32_bf16 v[4:7], v[172:175], v[212:215], v[4:7]
	v_mfma_f32_16x16x32_bf16 v[0:3], v[180:183], v[212:215], v[0:3]
	s_setprio 0
	s_barrier
	s_add_i32 s54, s54, 2
	s_add_u32 s52, s52, 0x100
	s_addc_u32 s53, s53, 0
	s_cmp_gt_u32 s54, 29
	s_mov_b64 s[46:47], s[6:7]
	s_cbranch_scc0 .LBB0_1727
	s_and_b64 vcc, exec, s[22:23]
	s_cbranch_vccz .LBB0_1730
	s_barrier

; #define PG8_STAGE(bufoff, gbase, voff) do { _Pragma("unroll") for (int _i = 0; _i < 2; ++_i) \
;         __builtin_amdgcn_global_load_lds((const unsigned*)((const char*)(gbase) + (voff)[_i]), (LAS unsigned*)(lds + (bufoff) + ldsw + _i * 8192), 16, 0, 0); } while (0)
; #define PG8_LDA(dst, b, h) do { _Pragma("unroll") for (int m = 0; m < 4; ++m) _Pragma("unroll") for (int k = 0; k < 2; ++k) dst[m][k] = *(const LAS bf16x8*)(lds + PG8_SA(b, h) + aoff + m * 2048 + k * 1024); } while (0)
; #define PG8_LDB(dst, b, h) do { _Pragma("unroll") for (int n = 0; n < 2; ++n) _Pragma("unroll") for (int k = 0; k < 2; ++k) dst[n][k] = *(const LAS bf16x8*)(lds + PG8_SB(b, h) + boff + n * 2048 + k * 1024); } while (0)
; #define PG8_MMA(ai, bj, At, Bt) do { __builtin_amdgcn_s_setprio(1); _Pragma("unroll") for (int m = 0; m < 4; ++m) _Pragma("unroll") for (int n = 0; n < 2; ++n) _Pragma("unroll") for (int k = 0; k < 2; ++k) \
;         acc[ai][bj][m][n] = __builtin_amdgcn_mfma_f32_16x16x32_bf16(Bt[n][k], At[m][k], acc[ai][bj][m][n], 0, 0, 0); __builtin_amdgcn_s_setprio(0); } while (0)
; #define PG8_WAIT_V(n) asm volatile("s_waitcnt vmcnt(" #n ")" ::: "memory")
; #define PG8_WAIT_L(n) asm volatile("s_waitcnt lgkmcnt(" #n ")" ::: "memory")
; #define PG8_BAR __builtin_amdgcn_s_barrier()
; #define PG8_SCHED __builtin_amdgcn_sched_barrier(0)
; template <class Epi>
; __device__ __forceinline__ void gemm_phase(LAS unsigned char* lds, const Gemm g, const StaticOrder& S, const Epi& E, const int wid) {
;     ...
;             PG8_LDB(B0, 0, 0); PG8_LDB(B1, 0, 1); PG8_SCHED; PG8_LDA(At, 0, 0); PG8_STAGE(PG8_SA(1, 1), a1 + hstepA, voffA);
;             PG8_WAIT_V(8); PG8_WAIT_L(0); PG8_BAR; PG8_MMA(0, 0, At, B0); PG8_MMA(0, 1, At, B1); PG8_BAR; PG8_SCHED;
;             PG8_LDA(At, 0, 1); PG8_STAGE(PG8_SB(0, 0), b2, voffB); PG8_STAGE(PG8_SB(0, 1), b2 + hstepB, voffB); PG8_STAGE(PG8_SA(0, 0), a2, voffA);
;             PG8_WAIT_V(8); PG8_WAIT_L(0); PG8_BAR; PG8_MMA(1, 0, At, B0); PG8_MMA(1, 1, At, B1); PG8_BAR; PG8_SCHED;
.LBB0_1773:
	ds_read_b128 v[150:153], v147
	ds_read_b128 v[154:157], v147 offset:1024
	ds_read_b128 v[158:161], v147 offset:2048
	ds_read_b128 v[162:165], v147 offset:3072
	ds_read_b128 v[166:169], v148
	ds_read_b128 v[170:173], v148 offset:1024
	ds_read_b128 v[174:177], v148 offset:2048
	ds_read_b128 v[178:181], v148 offset:3072
	s_add_u32 s6, s42, 0x100
	s_addc_u32 s7, s43, 0
	s_cmp_eq_u32 s54, 28
	s_cselect_b32 s47, s21, s7
	s_cselect_b32 s46, s20, s6
	s_cselect_b32 s45, s19, s53
	s_cselect_b32 s44, s51, s52
	s_add_i32 m0, s15, 0xc000
	ds_read_b128 v[182:185], v149
	global_load_lds_dwordx4 v136, s[42:43]
	s_add_i32 m0, s15, 0xe000
	ds_read_b128 v[186:189], v149 offset:1024
	global_load_lds_dwordx4 v138, s[42:43]
	ds_read_b128 v[190:193], v149 offset:2048
	ds_read_b128 v[194:197], v149 offset:3072
	ds_read_b128 v[198:201], v149 offset:4096
	ds_read_b128 v[202:205], v149 offset:5120
	ds_read_b128 v[206:209], v149 offset:6144
	ds_read_b128 v[210:213], v149 offset:7168
	s_waitcnt vmcnt(8)
	s_waitcnt lgkmcnt(0)
	s_barrier
	s_setprio 1
	s_waitcnt lgkmcnt(0)
	v_mfma_f32_16x16x32_bf16 v[124:127], v[150:153], v[182:185], v[124:127]
	v_mfma_f32_16x16x32_bf16 v[120:123], v[158:161], v[182:185], v[120:123]
	v_mfma_f32_16x16x32_bf16 v[108:111], v[150:153], v[190:193], v[108:111]
	v_mfma_f32_16x16x32_bf16 v[104:107], v[158:161], v[190:193], v[104:107]
	v_mfma_f32_16x16x32_bf16 v[92:95], v[150:153], v[198:201], v[92:95]
	v_mfma_f32_16x16x32_bf16 v[88:91], v[158:161], v[198:201], v[88:91]
	v_mfma_f32_16x16x32_bf16 v[76:79], v[150:153], v[206:209], v[76:79]
	v_mfma_f32_16x16x32_bf16 v[72:75], v[158:161], v[206:209], v[72:75]
	v_mfma_f32_16x16x32_bf16 v[124:127], v[154:157], v[186:189], v[124:127]
	v_mfma_f32_16x16x32_bf16 v[120:123], v[162:165], v[186:189], v[120:123]
	v_mfma_f32_16x16x32_bf16 v[108:111], v[154:157], v[194:197], v[108:111]
	v_mfma_f32_16x16x32_bf16 v[104:107], v[162:165], v[194:197], v[104:107]
	v_mfma_f32_16x16x32_bf16 v[92:95], v[154:157], v[202:205], v[92:95]
	v_mfma_f32_16x16x32_bf16 v[88:91], v[162:165], v[202:205], v[88:91]
	v_mfma_f32_16x16x32_bf16 v[76:79], v[154:157], v[210:213], v[76:79]
	v_mfma_f32_16x16x32_bf16 v[72:75], v[162:165], v[210:213], v[72:75]
	s_setprio 0
	s_setprio 1
	v_mfma_f32_16x16x32_bf16 v[116:119], v[166:169], v[182:185], v[116:119]
	v_mfma_f32_16x16x32_bf16 v[112:115], v[174:177], v[182:185], v[112:115]
	v_mfma_f32_16x16x32_bf16 v[100:103], v[166:169], v[190:193], v[100:103]
	v_mfma_f32_16x16x32_bf16 v[96:99], v[174:177], v[190:193], v[96:99]
	v_mfma_f32_16x16x32_bf16 v[84:87], v[166:169], v[198:201], v[84:87]
	v_mfma_f32_16x16x32_bf16 v[80:83], v[174:177], v[198:201], v[80:83]
	v_mfma_f32_16x16x32_bf16 v[68:71], v[166:169], v[206:209], v[68:71]
	v_mfma_f32_16x16x32_bf16 v[64:67], v[174:177], v[206:209], v[64:67]
	v_mfma_f32_16x16x32_bf16 v[116:119], v[170:173], v[186:189], v[116:119]
	v_mfma_f32_16x16x32_bf16 v[112:115], v[178:181], v[186:189], v[112:115]
	v_mfma_f32_16x16x32_bf16 v[100:103], v[170:173], v[194:197], v[100:103]
	v_mfma_f32_16x16x32_bf16 v[96:99], v[178:181], v[194:197], v[96:99]
	v_mfma_f32_16x16x32_bf16 v[84:87], v[170:173], v[202:205], v[84:87]
	v_mfma_f32_16x16x32_bf16 v[80:83], v[178:181], v[202:205], v[80:83]
	v_mfma_f32_16x16x32_bf16 v[68:71], v[170:173], v[210:213], v[68:71]
	v_mfma_f32_16x16x32_bf16 v[64:67], v[178:181], v[210:213], v[64:67]
	s_setprio 0
	s_barrier
	s_add_i32 s24, s36, s94
	s_mov_b32 m0, s24
	ds_read_b128 v[182:185], v149 offset:16384
	global_load_lds_dwordx4 v132, s[44:45]
	s_add_i32 m0, s24, 0x2000
	s_add_u32 s24, s44, 0x80000
	s_addc_u32 s25, s45, 0
	s_add_i32 s42, s37, s94
	global_load_lds_dwordx4 v128, s[44:45]
	s_mov_b32 m0, s42
	ds_read_b128 v[186:189], v149 offset:17408
	global_load_lds_dwordx4 v132, s[24:25]
	s_add_i32 m0, s42, 0x2000
	ds_read_b128 v[190:193], v149 offset:18432
	global_load_lds_dwordx4 v128, s[24:25]
	s_mov_b32 m0, s15
	ds_read_b128 v[194:197], v149 offset:19456
	global_load_lds_dwordx4 v134, s[46:47]
	s_mov_b32 m0, s26
	ds_read_b128 v[198:201], v149 offset:20480
	global_load_lds_dwordx4 v130, s[46:47]
	ds_read_b128 v[202:205], v149 offset:21504
	ds_read_b128 v[206:209], v149 offset:22528
	ds_read_b128 v[210:213], v149 offset:23552
	s_waitcnt vmcnt(8)
	s_waitcnt lgkmcnt(0)
	s_barrier
	s_setprio 1
	s_waitcnt lgkmcnt(0)
	v_mfma_f32_16x16x32_bf16 v[60:63], v[150:153], v[182:185], v[60:63]
	v_mfma_f32_16x16x32_bf16 v[56:59], v[158:161], v[182:185], v[56:59]
	v_mfma_f32_16x16x32_bf16 v[44:47], v[150:153], v[190:193], v[44:47]
	v_mfma_f32_16x16x32_bf16 v[40:43], v[158:161], v[190:193], v[40:43]
	v_mfma_f32_16x16x32_bf16 v[28:31], v[150:153], v[198:201], v[28:31]
	v_mfma_f32_16x16x32_bf16 v[24:27], v[158:161], v[198:201], v[24:27]
	v_mfma_f32_16x16x32_bf16 v[12:15], v[150:153], v[206:209], v[12:15]
	v_mfma_f32_16x16x32_bf16 v[8:11], v[158:161], v[206:209], v[8:11]
	v_mfma_f32_16x16x32_bf16 v[60:63], v[154:157], v[186:189], v[60:63]
	v_mfma_f32_16x16x32_bf16 v[56:59], v[162:165], v[186:189], v[56:59]
	v_mfma_f32_16x16x32_bf16 v[44:47], v[154:157], v[194:197], v[44:47]
	v_mfma_f32_16x16x32_bf16 v[40:43], v[162:165], v[194:197], v[40:43]
	v_mfma_f32_16x16x32_bf16 v[28:31], v[154:157], v[202:205], v[28:31]
	v_mfma_f32_16x16x32_bf16 v[24:27], v[162:165], v[202:205], v[24:27]
	v_mfma_f32_16x16x32_bf16 v[12:15], v[154:157], v[210:213], v[12:15]
	v_mfma_f32_16x16x32_bf16 v[8:11], v[162:165], v[210:213], v[8:11]
	s_setprio 0
	s_setprio 1
	v_mfma_f32_16x16x32_bf16 v[52:55], v[166:169], v[182:185], v[52:55]
	v_mfma_f32_16x16x32_bf16 v[48:51], v[174:177], v[182:185], v[48:51]
	v_mfma_f32_16x16x32_bf16 v[36:39], v[166:169], v[190:193], v[36:39]
	v_mfma_f32_16x16x32_bf16 v[32:35], v[174:177], v[190:193], v[32:35]
	v_mfma_f32_16x16x32_bf16 v[20:23], v[166:169], v[198:201], v[20:23]
	v_mfma_f32_16x16x32_bf16 v[16:19], v[174:177], v[198:201], v[16:19]
	v_mfma_f32_16x16x32_bf16 v[4:7], v[166:169], v[206:209], v[4:7]
	v_mfma_f32_16x16x32_bf16 v[0:3], v[174:177], v[206:209], v[0:3]
	v_mfma_f32_16x16x32_bf16 v[52:55], v[170:173], v[186:189], v[52:55]
	v_mfma_f32_16x16x32_bf16 v[48:51], v[178:181], v[186:189], v[48:51]
	v_mfma_f32_16x16x32_bf16 v[36:39], v[170:173], v[194:197], v[36:39]
	v_mfma_f32_16x16x32_bf16 v[32:35], v[178:181], v[194:197], v[32:35]
	v_mfma_f32_16x16x32_bf16 v[20:23], v[170:173], v[202:205], v[20:23]
	v_mfma_f32_16x16x32_bf16 v[16:19], v[178:181], v[202:205], v[16:19]
	v_mfma_f32_16x16x32_bf16 v[4:7], v[170:173], v[210:213], v[4:7]
	v_mfma_f32_16x16x32_bf16 v[0:3], v[178:181], v[210:213], v[0:3]
	s_setprio 0
	s_barrier
; #define PG8_STAGE(bufoff, gbase, voff) do { _Pragma("unroll") for (int _i = 0; _i < 2; ++_i) \
;         __builtin_amdgcn_global_load_lds((const unsigned*)((const char*)(gbase) + (voff)[_i]), (LAS unsigned*)(lds + (bufoff) + ldsw + _i * 8192), 16, 0, 0); } while (0)
; #define PG8_LDA(dst, b, h) do { _Pragma("unroll") for (int m = 0; m < 4; ++m) _Pragma("unroll") for (int k = 0; k < 2; ++k) dst[m][k] = *(const LAS bf16x8*)(lds + PG8_SA(b, h) + aoff + m * 2048 + k * 1024); } while (0)
; #define PG8_LDB(dst, b, h) do { _Pragma("unroll") for (int n = 0; n < 2; ++n) _Pragma("unroll") for (int k = 0; k < 2; ++k) dst[n][k] = *(const LAS bf16x8*)(lds + PG8_SB(b, h) + boff + n * 2048 + k * 1024); } while (0)
; #define PG8_MMA(ai, bj, At, Bt) do { __builtin_amdgcn_s_setprio(1); _Pragma("unroll") for (int m = 0; m < 4; ++m) _Pragma("unroll") for (int n = 0; n < 2; ++n) _Pragma("unroll") for (int k = 0; k < 2; ++k) \
;         acc[ai][bj][m][n] = __builtin_amdgcn_mfma_f32_16x16x32_bf16(Bt[n][k], At[m][k], acc[ai][bj][m][n], 0, 0, 0); __builtin_amdgcn_s_setprio(0); } while (0)
; #define PG8_WAIT_V(n) asm volatile("s_waitcnt vmcnt(" #n ")" ::: "memory")
; #define PG8_WAIT_L(n) asm volatile("s_waitcnt lgkmcnt(" #n ")" ::: "memory")
; #define PG8_BAR __builtin_amdgcn_s_barrier()
; #define PG8_SCHED __builtin_amdgcn_sched_barrier(0)
; template <class Epi>
; __device__ __forceinline__ void gemm_phase(LAS unsigned char* lds, const Gemm g, const StaticOrder& S, const Epi& E, const int wid) {
;     ...
;             PG8_LDB(B0, 1, 0); PG8_LDB(B1, 1, 1); PG8_SCHED; PG8_LDA(At, 1, 0); PG8_STAGE(PG8_SA(0, 1), a2 + hstepA, voffA);
;             PG8_WAIT_V(8); PG8_WAIT_L(0); PG8_BAR; PG8_MMA(0, 0, At, B0); PG8_MMA(0, 1, At, B1); PG8_BAR; PG8_SCHED;
;             PG8_LDA(At, 1, 1); PG8_STAGE(PG8_SB(1, 0), b3, voffB); PG8_STAGE(PG8_SB(1, 1), b3 + hstepB, voffB); PG8_STAGE(PG8_SA(1, 0), a3, voffA);
;             PG8_WAIT_V(8); PG8_WAIT_L(0); PG8_BAR; PG8_MMA(1, 0, At, B0); PG8_MMA(1, 1, At, B1); PG8_BAR; PG8_SCHED;
;         }
	s_add_i32 s42, 0, 0x18000
	s_add_i32 s43, 0, 0x1c000
	v_add_u32_e32 v162, s42, v144
	v_add_u32_e32 v178, s43, v144
	ds_read_b128 v[150:153], v162
	ds_read_b128 v[154:157], v162 offset:1024
	ds_read_b128 v[158:161], v162 offset:2048
	ds_read_b128 v[162:165], v162 offset:3072
	ds_read_b128 v[166:169], v178
	ds_read_b128 v[170:173], v178 offset:1024
	ds_read_b128 v[174:177], v178 offset:2048
	ds_read_b128 v[178:181], v178 offset:3072
	s_add_u32 s24, s46, 0x80000
	s_addc_u32 s25, s47, 0
	s_mov_b32 m0, s27
	ds_read_b128 v[182:185], v149 offset:32768
	global_load_lds_dwordx4 v134, s[24:25]
	s_mov_b32 m0, s28
	ds_read_b128 v[186:189], v149 offset:33792
	global_load_lds_dwordx4 v130, s[24:25]
	ds_read_b128 v[190:193], v149 offset:34816
	ds_read_b128 v[194:197], v149 offset:35840
	ds_read_b128 v[198:201], v149 offset:36864
	ds_read_b128 v[202:205], v149 offset:37888
	ds_read_b128 v[206:209], v149 offset:38912
	ds_read_b128 v[210:213], v149 offset:39936
	s_waitcnt vmcnt(8)
	s_waitcnt lgkmcnt(0)
	s_barrier
	s_setprio 1
	s_waitcnt lgkmcnt(0)
	v_mfma_f32_16x16x32_bf16 v[124:127], v[150:153], v[182:185], v[124:127]
	v_mfma_f32_16x16x32_bf16 v[120:123], v[158:161], v[182:185], v[120:123]
	v_mfma_f32_16x16x32_bf16 v[108:111], v[150:153], v[190:193], v[108:111]
	v_mfma_f32_16x16x32_bf16 v[104:107], v[158:161], v[190:193], v[104:107]
	v_mfma_f32_16x16x32_bf16 v[92:95], v[150:153], v[198:201], v[92:95]
	v_mfma_f32_16x16x32_bf16 v[88:91], v[158:161], v[198:201], v[88:91]
	v_mfma_f32_16x16x32_bf16 v[76:79], v[150:153], v[206:209], v[76:79]
	v_mfma_f32_16x16x32_bf16 v[72:75], v[158:161], v[206:209], v[72:75]
	v_mfma_f32_16x16x32_bf16 v[124:127], v[154:157], v[186:189], v[124:127]
	v_mfma_f32_16x16x32_bf16 v[120:123], v[162:165], v[186:189], v[120:123]
	v_mfma_f32_16x16x32_bf16 v[108:111], v[154:157], v[194:197], v[108:111]
	v_mfma_f32_16x16x32_bf16 v[104:107], v[162:165], v[194:197], v[104:107]
	v_mfma_f32_16x16x32_bf16 v[92:95], v[154:157], v[202:205], v[92:95]
	v_mfma_f32_16x16x32_bf16 v[88:91], v[162:165], v[202:205], v[88:91]
	v_mfma_f32_16x16x32_bf16 v[76:79], v[154:157], v[210:213], v[76:79]
	v_mfma_f32_16x16x32_bf16 v[72:75], v[162:165], v[210:213], v[72:75]
	s_setprio 0
	s_setprio 1
	v_mfma_f32_16x16x32_bf16 v[116:119], v[166:169], v[182:185], v[116:119]
	v_mfma_f32_16x16x32_bf16 v[112:115], v[174:177], v[182:185], v[112:115]
	v_mfma_f32_16x16x32_bf16 v[100:103], v[166:169], v[190:193], v[100:103]
	v_mfma_f32_16x16x32_bf16 v[96:99], v[174:177], v[190:193], v[96:99]
	v_mfma_f32_16x16x32_bf16 v[84:87], v[166:169], v[198:201], v[84:87]
	v_mfma_f32_16x16x32_bf16 v[80:83], v[174:177], v[198:201], v[80:83]
	v_mfma_f32_16x16x32_bf16 v[68:71], v[166:169], v[206:209], v[68:71]
	v_mfma_f32_16x16x32_bf16 v[64:67], v[174:177], v[206:209], v[64:67]
	v_mfma_f32_16x16x32_bf16 v[116:119], v[170:173], v[186:189], v[116:119]
	v_mfma_f32_16x16x32_bf16 v[112:115], v[178:181], v[186:189], v[112:115]
	v_mfma_f32_16x16x32_bf16 v[100:103], v[170:173], v[194:197], v[100:103]
	v_mfma_f32_16x16x32_bf16 v[96:99], v[178:181], v[194:197], v[96:99]
	v_mfma_f32_16x16x32_bf16 v[84:87], v[170:173], v[202:205], v[84:87]
	v_mfma_f32_16x16x32_bf16 v[80:83], v[178:181], v[202:205], v[80:83]
	v_mfma_f32_16x16x32_bf16 v[68:71], v[170:173], v[210:213], v[68:71]
	v_mfma_f32_16x16x32_bf16 v[64:67], v[178:181], v[210:213], v[64:67]
	s_setprio 0
	s_barrier
	s_add_i32 s24, s42, s94
	s_add_u32 s98, s44, 0x80
	s_addc_u32 s99, s45, 0
	s_mov_b32 m0, s24
	ds_read_b128 v[182:185], v149 offset:49152
	global_load_lds_dwordx4 v132, s[98:99]
	s_add_i32 m0, s24, 0x2000
	s_add_u32 s24, s44, 0x80080
	s_addc_u32 s25, s45, 0
	s_add_i32 s42, s43, s94
	global_load_lds_dwordx4 v128, s[98:99]
	s_mov_b32 m0, s42
	ds_read_b128 v[186:189], v149 offset:50176
	global_load_lds_dwordx4 v132, s[24:25]
	s_add_i32 m0, s42, 0x2000
	ds_read_b128 v[190:193], v149 offset:51200
	global_load_lds_dwordx4 v128, s[24:25]
	s_add_u32 s100, s46, 0x80
	s_addc_u32 s101, s47, 0
	s_mov_b32 m0, s34
	ds_read_b128 v[194:197], v149 offset:52224
	global_load_lds_dwordx4 v134, s[100:101]
	s_mov_b32 m0, s35
	ds_read_b128 v[198:201], v149 offset:53248
	global_load_lds_dwordx4 v130, s[100:101]
	ds_read_b128 v[202:205], v149 offset:54272
	ds_read_b128 v[206:209], v149 offset:55296
	ds_read_b128 v[210:213], v149 offset:56320
	s_waitcnt vmcnt(8)
	s_waitcnt lgkmcnt(0)
	s_barrier
	s_setprio 1
	s_waitcnt lgkmcnt(0)
	v_mfma_f32_16x16x32_bf16 v[60:63], v[150:153], v[182:185], v[60:63]
	v_mfma_f32_16x16x32_bf16 v[56:59], v[158:161], v[182:185], v[56:59]
	v_mfma_f32_16x16x32_bf16 v[44:47], v[150:153], v[190:193], v[44:47]
	v_mfma_f32_16x16x32_bf16 v[40:43], v[158:161], v[190:193], v[40:43]
	v_mfma_f32_16x16x32_bf16 v[28:31], v[150:153], v[198:201], v[28:31]
	v_mfma_f32_16x16x32_bf16 v[24:27], v[158:161], v[198:201], v[24:27]
	v_mfma_f32_16x16x32_bf16 v[12:15], v[150:153], v[206:209], v[12:15]
	v_mfma_f32_16x16x32_bf16 v[8:11], v[158:161], v[206:209], v[8:11]
	v_mfma_f32_16x16x32_bf16 v[60:63], v[154:157], v[186:189], v[60:63]
	v_mfma_f32_16x16x32_bf16 v[56:59], v[162:165], v[186:189], v[56:59]
	v_mfma_f32_16x16x32_bf16 v[44:47], v[154:157], v[194:197], v[44:47]
	v_mfma_f32_16x16x32_bf16 v[40:43], v[162:165], v[194:197], v[40:43]
	v_mfma_f32_16x16x32_bf16 v[28:31], v[154:157], v[202:205], v[28:31]
	v_mfma_f32_16x16x32_bf16 v[24:27], v[162:165], v[202:205], v[24:27]
	v_mfma_f32_16x16x32_bf16 v[12:15], v[154:157], v[210:213], v[12:15]
	v_mfma_f32_16x16x32_bf16 v[8:11], v[162:165], v[210:213], v[8:11]
	s_setprio 0
	s_setprio 1
	v_mfma_f32_16x16x32_bf16 v[52:55], v[166:169], v[182:185], v[52:55]
	v_mfma_f32_16x16x32_bf16 v[48:51], v[174:177], v[182:185], v[48:51]
	v_mfma_f32_16x16x32_bf16 v[36:39], v[166:169], v[190:193], v[36:39]
	v_mfma_f32_16x16x32_bf16 v[32:35], v[174:177], v[190:193], v[32:35]
	v_mfma_f32_16x16x32_bf16 v[20:23], v[166:169], v[198:201], v[20:23]
	v_mfma_f32_16x16x32_bf16 v[16:19], v[174:177], v[198:201], v[16:19]
	v_mfma_f32_16x16x32_bf16 v[4:7], v[166:169], v[206:209], v[4:7]
	v_mfma_f32_16x16x32_bf16 v[0:3], v[174:177], v[206:209], v[0:3]
	v_mfma_f32_16x16x32_bf16 v[52:55], v[170:173], v[186:189], v[52:55]
	v_mfma_f32_16x16x32_bf16 v[48:51], v[178:181], v[186:189], v[48:51]
	v_mfma_f32_16x16x32_bf16 v[36:39], v[170:173], v[194:197], v[36:39]
	v_mfma_f32_16x16x32_bf16 v[32:35], v[178:181], v[194:197], v[32:35]
	v_mfma_f32_16x16x32_bf16 v[20:23], v[170:173], v[202:205], v[20:23]
	v_mfma_f32_16x16x32_bf16 v[16:19], v[178:181], v[202:205], v[16:19]
	v_mfma_f32_16x16x32_bf16 v[4:7], v[170:173], v[210:213], v[4:7]
	v_mfma_f32_16x16x32_bf16 v[0:3], v[178:181], v[210:213], v[0:3]
	s_setprio 0
	s_barrier
	s_add_i32 s54, s54, 2
	s_add_u32 s52, s52, 0x100
	s_addc_u32 s53, s53, 0
	s_cmp_gt_u32 s54, 29
	s_mov_b64 s[42:43], s[6:7]
	s_cbranch_scc0 .LBB0_1773
	s_and_b64 vcc, exec, s[22:23]
	s_cbranch_vccz .LBB0_1776
	s_barrier

; #define PG8_STAGE(bufoff, gbase, voff) do { _Pragma("unroll") for (int _i = 0; _i < 2; ++_i) \
;         __builtin_amdgcn_global_load_lds((const unsigned*)((const char*)(gbase) + (voff)[_i]), (LAS unsigned*)(lds + (bufoff) + ldsw + _i * 8192), 16, 0, 0); } while (0)
; #define PG8_LDA(dst, b, h) do { _Pragma("unroll") for (int m = 0; m < 4; ++m) _Pragma("unroll") for (int k = 0; k < 2; ++k) dst[m][k] = *(const LAS bf16x8*)(lds + PG8_SA(b, h) + aoff + m * 2048 + k * 1024); } while (0)
; #define PG8_LDB(dst, b, h) do { _Pragma("unroll") for (int n = 0; n < 2; ++n) _Pragma("unroll") for (int k = 0; k < 2; ++k) dst[n][k] = *(const LAS bf16x8*)(lds + PG8_SB(b, h) + boff + n * 2048 + k * 1024); } while (0)
; #define PG8_MMA(ai, bj, At, Bt) do { __builtin_amdgcn_s_setprio(1); _Pragma("unroll") for (int m = 0; m < 4; ++m) _Pragma("unroll") for (int n = 0; n < 2; ++n) _Pragma("unroll") for (int k = 0; k < 2; ++k) \
;         acc[ai][bj][m][n] = __builtin_amdgcn_mfma_f32_16x16x32_bf16(Bt[n][k], At[m][k], acc[ai][bj][m][n], 0, 0, 0); __builtin_amdgcn_s_setprio(0); } while (0)
; #define PG8_WAIT_V(n) asm volatile("s_waitcnt vmcnt(" #n ")" ::: "memory")
; #define PG8_WAIT_L(n) asm volatile("s_waitcnt lgkmcnt(" #n ")" ::: "memory")
; #define PG8_BAR __builtin_amdgcn_s_barrier()
; #define PG8_SCHED __builtin_amdgcn_sched_barrier(0)
; template <class Epi>
; __device__ __forceinline__ void gemm_phase(LAS unsigned char* lds, const Gemm g, const StaticOrder& S, const Epi& E, const int wid) {
;     ...
;             PG8_LDB(B0, 0, 0); PG8_LDB(B1, 0, 1); PG8_SCHED; PG8_LDA(At, 0, 0); PG8_STAGE(PG8_SA(1, 1), a1 + hstepA, voffA);
;             PG8_WAIT_V(8); PG8_WAIT_L(0); PG8_BAR; PG8_MMA(0, 0, At, B0); PG8_MMA(0, 1, At, B1); PG8_BAR; PG8_SCHED;
;             PG8_LDA(At, 0, 1); PG8_STAGE(PG8_SB(0, 0), b2, voffB); PG8_STAGE(PG8_SB(0, 1), b2 + hstepB, voffB); PG8_STAGE(PG8_SA(0, 0), a2, voffA);
;             PG8_WAIT_V(8); PG8_WAIT_L(0); PG8_BAR; PG8_MMA(1, 0, At, B0); PG8_MMA(1, 1, At, B1); PG8_BAR; PG8_SCHED;
.LBB0_1810:
	ds_read_b128 v[144:147], v153
	ds_read_b128 v[156:159], v153 offset:1024
	ds_read_b128 v[160:163], v153 offset:2048
	ds_read_b128 v[164:167], v153 offset:3072
	ds_read_b128 v[168:171], v154
	ds_read_b128 v[172:175], v154 offset:1024
	ds_read_b128 v[176:179], v154 offset:2048
	ds_read_b128 v[180:183], v154 offset:3072
	s_add_u32 s26, s20, 0x100
	s_addc_u32 s27, s21, 0
	s_cmpk_eq_i32 s45, 0x54
	s_cselect_b32 s31, s7, s27
	s_cselect_b32 s30, s6, s26
	s_cselect_b32 s29, s19, s44
	s_cselect_b32 s28, s18, s43
	s_add_i32 m0, s1, 0xc000
	ds_read_b128 v[184:187], v155
	global_load_lds_dwordx4 v136, s[20:21]
	s_add_i32 m0, s1, 0xe000
	ds_read_b128 v[188:191], v155 offset:1024
	global_load_lds_dwordx4 v138, s[20:21]
	ds_read_b128 v[192:195], v155 offset:2048
	ds_read_b128 v[196:199], v155 offset:3072
	ds_read_b128 v[200:203], v155 offset:4096
	ds_read_b128 v[204:207], v155 offset:5120
	ds_read_b128 v[208:211], v155 offset:6144
	ds_read_b128 v[212:215], v155 offset:7168
	s_waitcnt vmcnt(8)
	s_waitcnt lgkmcnt(0)
	s_barrier
	s_setprio 1
	s_waitcnt lgkmcnt(0)
	v_mfma_f32_16x16x32_bf16 v[124:127], v[144:147], v[184:187], v[124:127]
	v_mfma_f32_16x16x32_bf16 v[120:123], v[160:163], v[184:187], v[120:123]
	v_mfma_f32_16x16x32_bf16 v[116:119], v[144:147], v[192:195], v[116:119]
	v_mfma_f32_16x16x32_bf16 v[112:115], v[160:163], v[192:195], v[112:115]
	v_mfma_f32_16x16x32_bf16 v[108:111], v[144:147], v[200:203], v[108:111]
	v_mfma_f32_16x16x32_bf16 v[104:107], v[160:163], v[200:203], v[104:107]
	v_mfma_f32_16x16x32_bf16 v[100:103], v[144:147], v[208:211], v[100:103]
	v_mfma_f32_16x16x32_bf16 v[96:99], v[160:163], v[208:211], v[96:99]
	v_mfma_f32_16x16x32_bf16 v[124:127], v[156:159], v[188:191], v[124:127]
	v_mfma_f32_16x16x32_bf16 v[120:123], v[164:167], v[188:191], v[120:123]
	v_mfma_f32_16x16x32_bf16 v[116:119], v[156:159], v[196:199], v[116:119]
	v_mfma_f32_16x16x32_bf16 v[112:115], v[164:167], v[196:199], v[112:115]
	v_mfma_f32_16x16x32_bf16 v[108:111], v[156:159], v[204:207], v[108:111]
	v_mfma_f32_16x16x32_bf16 v[104:107], v[164:167], v[204:207], v[104:107]
	v_mfma_f32_16x16x32_bf16 v[100:103], v[156:159], v[212:215], v[100:103]
	v_mfma_f32_16x16x32_bf16 v[96:99], v[164:167], v[212:215], v[96:99]
	s_setprio 0
	s_setprio 1
	v_mfma_f32_16x16x32_bf16 v[68:71], v[168:171], v[184:187], v[68:71]
	v_mfma_f32_16x16x32_bf16 v[64:67], v[176:179], v[184:187], v[64:67]
	v_mfma_f32_16x16x32_bf16 v[52:55], v[168:171], v[192:195], v[52:55]
	v_mfma_f32_16x16x32_bf16 v[48:51], v[176:179], v[192:195], v[48:51]
	v_mfma_f32_16x16x32_bf16 v[44:47], v[168:171], v[200:203], v[44:47]
	v_mfma_f32_16x16x32_bf16 v[40:43], v[176:179], v[200:203], v[40:43]
	v_mfma_f32_16x16x32_bf16 v[36:39], v[168:171], v[208:211], v[36:39]
	v_mfma_f32_16x16x32_bf16 v[32:35], v[176:179], v[208:211], v[32:35]
	v_mfma_f32_16x16x32_bf16 v[68:71], v[172:175], v[188:191], v[68:71]
	v_mfma_f32_16x16x32_bf16 v[64:67], v[180:183], v[188:191], v[64:67]
	v_mfma_f32_16x16x32_bf16 v[52:55], v[172:175], v[196:199], v[52:55]
	v_mfma_f32_16x16x32_bf16 v[48:51], v[180:183], v[196:199], v[48:51]
	v_mfma_f32_16x16x32_bf16 v[44:47], v[172:175], v[204:207], v[44:47]
	v_mfma_f32_16x16x32_bf16 v[40:43], v[180:183], v[204:207], v[40:43]
	v_mfma_f32_16x16x32_bf16 v[36:39], v[172:175], v[212:215], v[36:39]
	v_mfma_f32_16x16x32_bf16 v[32:35], v[180:183], v[212:215], v[32:35]
	s_setprio 0
	s_barrier
	s_add_i32 s20, s0, s94
	s_mov_b32 m0, s20
	ds_read_b128 v[184:187], v155 offset:16384
	global_load_lds_dwordx4 v132, s[28:29]
	s_add_i32 m0, s20, 0x2000
	s_add_u32 s20, s28, 0x160000
	s_addc_u32 s21, s29, 0
	s_add_i32 s24, s38, s94
	global_load_lds_dwordx4 v128, s[28:29]
	s_mov_b32 m0, s24
	ds_read_b128 v[188:191], v155 offset:17408
	global_load_lds_dwordx4 v132, s[20:21]
	s_add_i32 m0, s24, 0x2000
	ds_read_b128 v[192:195], v155 offset:18432
	global_load_lds_dwordx4 v128, s[20:21]
	s_mov_b32 m0, s1
	ds_read_b128 v[196:199], v155 offset:19456
	global_load_lds_dwordx4 v134, s[30:31]
	s_mov_b32 m0, s12
	ds_read_b128 v[200:203], v155 offset:20480
	global_load_lds_dwordx4 v130, s[30:31]
	ds_read_b128 v[204:207], v155 offset:21504
	ds_read_b128 v[208:211], v155 offset:22528
	ds_read_b128 v[212:215], v155 offset:23552
	s_waitcnt vmcnt(8)
	s_waitcnt lgkmcnt(0)
	s_barrier
	s_setprio 1
	s_waitcnt lgkmcnt(0)
	v_mfma_f32_16x16x32_bf16 v[92:95], v[144:147], v[184:187], v[92:95]
	v_mfma_f32_16x16x32_bf16 v[88:91], v[160:163], v[184:187], v[88:91]
	v_mfma_f32_16x16x32_bf16 v[84:87], v[144:147], v[192:195], v[84:87]
	v_mfma_f32_16x16x32_bf16 v[80:83], v[160:163], v[192:195], v[80:83]
	v_mfma_f32_16x16x32_bf16 v[76:79], v[144:147], v[200:203], v[76:79]
	v_mfma_f32_16x16x32_bf16 v[72:75], v[160:163], v[200:203], v[72:75]
	v_mfma_f32_16x16x32_bf16 v[60:63], v[144:147], v[208:211], v[60:63]
	v_mfma_f32_16x16x32_bf16 v[56:59], v[160:163], v[208:211], v[56:59]
	v_mfma_f32_16x16x32_bf16 v[92:95], v[156:159], v[188:191], v[92:95]
	v_mfma_f32_16x16x32_bf16 v[88:91], v[164:167], v[188:191], v[88:91]
	v_mfma_f32_16x16x32_bf16 v[84:87], v[156:159], v[196:199], v[84:87]
	v_mfma_f32_16x16x32_bf16 v[80:83], v[164:167], v[196:199], v[80:83]
	v_mfma_f32_16x16x32_bf16 v[76:79], v[156:159], v[204:207], v[76:79]
	v_mfma_f32_16x16x32_bf16 v[72:75], v[164:167], v[204:207], v[72:75]
	v_mfma_f32_16x16x32_bf16 v[60:63], v[156:159], v[212:215], v[60:63]
	v_mfma_f32_16x16x32_bf16 v[56:59], v[164:167], v[212:215], v[56:59]
	s_setprio 0
	s_setprio 1
	v_mfma_f32_16x16x32_bf16 v[28:31], v[168:171], v[184:187], v[28:31]
	v_mfma_f32_16x16x32_bf16 v[24:27], v[176:179], v[184:187], v[24:27]
	v_mfma_f32_16x16x32_bf16 v[20:23], v[168:171], v[192:195], v[20:23]
	v_mfma_f32_16x16x32_bf16 v[16:19], v[176:179], v[192:195], v[16:19]
	v_mfma_f32_16x16x32_bf16 v[12:15], v[168:171], v[200:203], v[12:15]
	v_mfma_f32_16x16x32_bf16 v[8:11], v[176:179], v[200:203], v[8:11]
	v_mfma_f32_16x16x32_bf16 v[4:7], v[168:171], v[208:211], v[4:7]
	v_mfma_f32_16x16x32_bf16 v[0:3], v[176:179], v[208:211], v[0:3]
	v_mfma_f32_16x16x32_bf16 v[28:31], v[172:175], v[188:191], v[28:31]
	v_mfma_f32_16x16x32_bf16 v[24:27], v[180:183], v[188:191], v[24:27]
	v_mfma_f32_16x16x32_bf16 v[20:23], v[172:175], v[196:199], v[20:23]
	v_mfma_f32_16x16x32_bf16 v[16:19], v[180:183], v[196:199], v[16:19]
	v_mfma_f32_16x16x32_bf16 v[12:15], v[172:175], v[204:207], v[12:15]
	v_mfma_f32_16x16x32_bf16 v[8:11], v[180:183], v[204:207], v[8:11]
	v_mfma_f32_16x16x32_bf16 v[4:7], v[172:175], v[212:215], v[4:7]
	v_mfma_f32_16x16x32_bf16 v[0:3], v[180:183], v[212:215], v[0:3]
	s_setprio 0
	s_barrier
; #define PG8_STAGE(bufoff, gbase, voff) do { _Pragma("unroll") for (int _i = 0; _i < 2; ++_i) \
;         __builtin_amdgcn_global_load_lds((const unsigned*)((const char*)(gbase) + (voff)[_i]), (LAS unsigned*)(lds + (bufoff) + ldsw + _i * 8192), 16, 0, 0); } while (0)
; #define PG8_LDA(dst, b, h) do { _Pragma("unroll") for (int m = 0; m < 4; ++m) _Pragma("unroll") for (int k = 0; k < 2; ++k) dst[m][k] = *(const LAS bf16x8*)(lds + PG8_SA(b, h) + aoff + m * 2048 + k * 1024); } while (0)
; #define PG8_LDB(dst, b, h) do { _Pragma("unroll") for (int n = 0; n < 2; ++n) _Pragma("unroll") for (int k = 0; k < 2; ++k) dst[n][k] = *(const LAS bf16x8*)(lds + PG8_SB(b, h) + boff + n * 2048 + k * 1024); } while (0)
; #define PG8_MMA(ai, bj, At, Bt) do { __builtin_amdgcn_s_setprio(1); _Pragma("unroll") for (int m = 0; m < 4; ++m) _Pragma("unroll") for (int n = 0; n < 2; ++n) _Pragma("unroll") for (int k = 0; k < 2; ++k) \
;         acc[ai][bj][m][n] = __builtin_amdgcn_mfma_f32_16x16x32_bf16(Bt[n][k], At[m][k], acc[ai][bj][m][n], 0, 0, 0); __builtin_amdgcn_s_setprio(0); } while (0)
; #define PG8_WAIT_V(n) asm volatile("s_waitcnt vmcnt(" #n ")" ::: "memory")
; #define PG8_WAIT_L(n) asm volatile("s_waitcnt lgkmcnt(" #n ")" ::: "memory")
; #define PG8_BAR __builtin_amdgcn_s_barrier()
; #define PG8_SCHED __builtin_amdgcn_sched_barrier(0)
; template <class Epi>
; __device__ __forceinline__ void gemm_phase(LAS unsigned char* lds, const Gemm g, const StaticOrder& S, const Epi& E, const int wid) {
;     ...
;             PG8_LDB(B0, 1, 0); PG8_LDB(B1, 1, 1); PG8_SCHED; PG8_LDA(At, 1, 0); PG8_STAGE(PG8_SA(0, 1), a2 + hstepA, voffA);
;             PG8_WAIT_V(8); PG8_WAIT_L(0); PG8_BAR; PG8_MMA(0, 0, At, B0); PG8_MMA(0, 1, At, B1); PG8_BAR; PG8_SCHED;
;             PG8_LDA(At, 1, 1); PG8_STAGE(PG8_SB(1, 0), b3, voffB); PG8_STAGE(PG8_SB(1, 1), b3 + hstepB, voffB); PG8_STAGE(PG8_SA(1, 0), a3, voffA);
;             PG8_WAIT_V(8); PG8_WAIT_L(0); PG8_BAR; PG8_MMA(1, 0, At, B0); PG8_MMA(1, 1, At, B1); PG8_BAR; PG8_SCHED;
;         }
	s_add_i32 s24, 0, 0x18000
	s_add_i32 s25, 0, 0x1c000
	v_add_u32_e32 v164, s24, v150
	v_add_u32_e32 v180, s25, v150
	ds_read_b128 v[144:147], v164
	ds_read_b128 v[156:159], v164 offset:1024
	ds_read_b128 v[160:163], v164 offset:2048
	ds_read_b128 v[164:167], v164 offset:3072
	ds_read_b128 v[168:171], v180
	ds_read_b128 v[172:175], v180 offset:1024
	ds_read_b128 v[176:179], v180 offset:2048
	ds_read_b128 v[180:183], v180 offset:3072
	s_add_u32 s20, s30, 0x160000
	s_addc_u32 s21, s31, 0
	s_mov_b32 m0, s15
	ds_read_b128 v[184:187], v155 offset:32768
	global_load_lds_dwordx4 v134, s[20:21]
	s_mov_b32 m0, s34
	ds_read_b128 v[188:191], v155 offset:33792
	global_load_lds_dwordx4 v130, s[20:21]
	ds_read_b128 v[192:195], v155 offset:34816
	ds_read_b128 v[196:199], v155 offset:35840
	ds_read_b128 v[200:203], v155 offset:36864
	ds_read_b128 v[204:207], v155 offset:37888
	ds_read_b128 v[208:211], v155 offset:38912
	ds_read_b128 v[212:215], v155 offset:39936
	s_waitcnt vmcnt(8)
	s_waitcnt lgkmcnt(0)
	s_barrier
	s_setprio 1
	s_waitcnt lgkmcnt(0)
	v_mfma_f32_16x16x32_bf16 v[124:127], v[144:147], v[184:187], v[124:127]
	v_mfma_f32_16x16x32_bf16 v[120:123], v[160:163], v[184:187], v[120:123]
	v_mfma_f32_16x16x32_bf16 v[116:119], v[144:147], v[192:195], v[116:119]
	v_mfma_f32_16x16x32_bf16 v[112:115], v[160:163], v[192:195], v[112:115]
	v_mfma_f32_16x16x32_bf16 v[108:111], v[144:147], v[200:203], v[108:111]
	v_mfma_f32_16x16x32_bf16 v[104:107], v[160:163], v[200:203], v[104:107]
	v_mfma_f32_16x16x32_bf16 v[100:103], v[144:147], v[208:211], v[100:103]
	v_mfma_f32_16x16x32_bf16 v[96:99], v[160:163], v[208:211], v[96:99]
	v_mfma_f32_16x16x32_bf16 v[124:127], v[156:159], v[188:191], v[124:127]
	v_mfma_f32_16x16x32_bf16 v[120:123], v[164:167], v[188:191], v[120:123]
	v_mfma_f32_16x16x32_bf16 v[116:119], v[156:159], v[196:199], v[116:119]
	v_mfma_f32_16x16x32_bf16 v[112:115], v[164:167], v[196:199], v[112:115]
	v_mfma_f32_16x16x32_bf16 v[108:111], v[156:159], v[204:207], v[108:111]
	v_mfma_f32_16x16x32_bf16 v[104:107], v[164:167], v[204:207], v[104:107]
	v_mfma_f32_16x16x32_bf16 v[100:103], v[156:159], v[212:215], v[100:103]
	v_mfma_f32_16x16x32_bf16 v[96:99], v[164:167], v[212:215], v[96:99]
	s_setprio 0
	s_setprio 1
	v_mfma_f32_16x16x32_bf16 v[68:71], v[168:171], v[184:187], v[68:71]
	v_mfma_f32_16x16x32_bf16 v[64:67], v[176:179], v[184:187], v[64:67]
	v_mfma_f32_16x16x32_bf16 v[52:55], v[168:171], v[192:195], v[52:55]
	v_mfma_f32_16x16x32_bf16 v[48:51], v[176:179], v[192:195], v[48:51]
	v_mfma_f32_16x16x32_bf16 v[44:47], v[168:171], v[200:203], v[44:47]
	v_mfma_f32_16x16x32_bf16 v[40:43], v[176:179], v[200:203], v[40:43]
	v_mfma_f32_16x16x32_bf16 v[36:39], v[168:171], v[208:211], v[36:39]
	v_mfma_f32_16x16x32_bf16 v[32:35], v[176:179], v[208:211], v[32:35]
	v_mfma_f32_16x16x32_bf16 v[68:71], v[172:175], v[188:191], v[68:71]
	v_mfma_f32_16x16x32_bf16 v[64:67], v[180:183], v[188:191], v[64:67]
	v_mfma_f32_16x16x32_bf16 v[52:55], v[172:175], v[196:199], v[52:55]
	v_mfma_f32_16x16x32_bf16 v[48:51], v[180:183], v[196:199], v[48:51]
	v_mfma_f32_16x16x32_bf16 v[44:47], v[172:175], v[204:207], v[44:47]
	v_mfma_f32_16x16x32_bf16 v[40:43], v[180:183], v[204:207], v[40:43]
	v_mfma_f32_16x16x32_bf16 v[36:39], v[172:175], v[212:215], v[36:39]
	v_mfma_f32_16x16x32_bf16 v[32:35], v[180:183], v[212:215], v[32:35]
	s_setprio 0
	s_barrier
	s_add_i32 s20, s24, s94
	s_add_u32 s98, s28, 0x80
	s_addc_u32 s99, s29, 0
	s_mov_b32 m0, s20
	ds_read_b128 v[184:187], v155 offset:49152
	global_load_lds_dwordx4 v132, s[98:99]
	s_add_i32 m0, s20, 0x2000
	s_add_u32 s20, s28, 0x160080
	s_addc_u32 s21, s29, 0
	s_add_i32 s24, s25, s94
	global_load_lds_dwordx4 v128, s[98:99]
	s_mov_b32 m0, s24
	ds_read_b128 v[188:191], v155 offset:50176
	global_load_lds_dwordx4 v132, s[20:21]
	s_add_i32 m0, s24, 0x2000
	ds_read_b128 v[192:195], v155 offset:51200
	global_load_lds_dwordx4 v128, s[20:21]
	s_add_u32 s100, s30, 0x80
	s_addc_u32 s101, s31, 0
	s_mov_b32 m0, s36
	ds_read_b128 v[196:199], v155 offset:52224
	global_load_lds_dwordx4 v134, s[100:101]
	s_mov_b32 m0, s37
	ds_read_b128 v[200:203], v155 offset:53248
	global_load_lds_dwordx4 v130, s[100:101]
	ds_read_b128 v[204:207], v155 offset:54272
	ds_read_b128 v[208:211], v155 offset:55296
	ds_read_b128 v[212:215], v155 offset:56320
	s_waitcnt vmcnt(8)
	s_waitcnt lgkmcnt(0)
	s_barrier
	s_setprio 1
	s_waitcnt lgkmcnt(0)
	v_mfma_f32_16x16x32_bf16 v[92:95], v[144:147], v[184:187], v[92:95]
	v_mfma_f32_16x16x32_bf16 v[88:91], v[160:163], v[184:187], v[88:91]
	v_mfma_f32_16x16x32_bf16 v[84:87], v[144:147], v[192:195], v[84:87]
	v_mfma_f32_16x16x32_bf16 v[80:83], v[160:163], v[192:195], v[80:83]
	v_mfma_f32_16x16x32_bf16 v[76:79], v[144:147], v[200:203], v[76:79]
	v_mfma_f32_16x16x32_bf16 v[72:75], v[160:163], v[200:203], v[72:75]
	v_mfma_f32_16x16x32_bf16 v[60:63], v[144:147], v[208:211], v[60:63]
	v_mfma_f32_16x16x32_bf16 v[56:59], v[160:163], v[208:211], v[56:59]
	v_mfma_f32_16x16x32_bf16 v[92:95], v[156:159], v[188:191], v[92:95]
	v_mfma_f32_16x16x32_bf16 v[88:91], v[164:167], v[188:191], v[88:91]
	v_mfma_f32_16x16x32_bf16 v[84:87], v[156:159], v[196:199], v[84:87]
	v_mfma_f32_16x16x32_bf16 v[80:83], v[164:167], v[196:199], v[80:83]
	v_mfma_f32_16x16x32_bf16 v[76:79], v[156:159], v[204:207], v[76:79]
	v_mfma_f32_16x16x32_bf16 v[72:75], v[164:167], v[204:207], v[72:75]
	v_mfma_f32_16x16x32_bf16 v[60:63], v[156:159], v[212:215], v[60:63]
	v_mfma_f32_16x16x32_bf16 v[56:59], v[164:167], v[212:215], v[56:59]
	s_setprio 0
	s_setprio 1
	v_mfma_f32_16x16x32_bf16 v[28:31], v[168:171], v[184:187], v[28:31]
	v_mfma_f32_16x16x32_bf16 v[24:27], v[176:179], v[184:187], v[24:27]
	v_mfma_f32_16x16x32_bf16 v[20:23], v[168:171], v[192:195], v[20:23]
	v_mfma_f32_16x16x32_bf16 v[16:19], v[176:179], v[192:195], v[16:19]
	v_mfma_f32_16x16x32_bf16 v[12:15], v[168:171], v[200:203], v[12:15]
	v_mfma_f32_16x16x32_bf16 v[8:11], v[176:179], v[200:203], v[8:11]
	v_mfma_f32_16x16x32_bf16 v[4:7], v[168:171], v[208:211], v[4:7]
	v_mfma_f32_16x16x32_bf16 v[0:3], v[176:179], v[208:211], v[0:3]
	v_mfma_f32_16x16x32_bf16 v[28:31], v[172:175], v[188:191], v[28:31]
	v_mfma_f32_16x16x32_bf16 v[24:27], v[180:183], v[188:191], v[24:27]
	v_mfma_f32_16x16x32_bf16 v[20:23], v[172:175], v[196:199], v[20:23]
	v_mfma_f32_16x16x32_bf16 v[16:19], v[180:183], v[196:199], v[16:19]
	v_mfma_f32_16x16x32_bf16 v[12:15], v[172:175], v[204:207], v[12:15]
	v_mfma_f32_16x16x32_bf16 v[8:11], v[180:183], v[204:207], v[8:11]
	v_mfma_f32_16x16x32_bf16 v[4:7], v[172:175], v[212:215], v[4:7]
	v_mfma_f32_16x16x32_bf16 v[0:3], v[180:183], v[212:215], v[0:3]
	s_setprio 0
	s_barrier
	s_add_i32 s45, s45, 2
	s_add_u32 s43, s43, 0x100
	s_addc_u32 s44, s44, 0
	s_cmpk_gt_u32 s45, 0x55
	s_mov_b64 s[20:21], s[26:27]
	s_cbranch_scc0 .LBB0_1810
	s_and_b64 vcc, exec, s[22:23]
	s_cbranch_vccz .LBB0_1813
	s_barrier
